# weight-conversion tile loops at the attention tail: loads for 3 tiles issued up front into spare VGPRs, then processed one by one (8 of 9 loop instances)
# speedup vs baseline: 1.0037x; 1.0037x over previous
;     ...
;   for (int t = blockIdx.x; t < ntk * ntn; t += gridDim.x) {
;     const int tk = t % ntk, tn = t / ntk, k0 = tk * 64, n0 = tn * 64;
;     __syncthreads();
; #pragma unroll
;     for (int i = 0; i < 2; ++i) {
;       const int id = tid + 512 * i, kr = id >> 4, n4 = (id & 15) * 4;
;       f32x4 v = {0.f, 0.f, 0.f, 0.f};
;       const int nd = n0 + n4, nsrc = (nvalid < 0) ? nd : (nd < csplit ? nd + coff1 : nd + coff2);
;       if (nd < ((nvalid < 0) ? N : nvalid)) v = *(const f32x4*)(W + (size_t)(k0 + kr) * N + nsrc);
;       tile[kr * 65 + n4 + 0] = v[0]; tile[kr * 65 + n4 + 1] = v[1]; tile[kr * 65 + n4 + 2] = v[2]; tile[kr * 65 + n4 + 3] = v[3];
;     }
;     __syncthreads();
;     {
;       const int n = tid >> 3, c = tid & 7;
;       bool rot = false;
;       if (PERM == 1) rot = (n0 == rot_n0);
;       if (PERM == 2) rot = ((tn % 3) == 2);
;       const int ns = rot ? ((n >> 1) + 32 * (n & 1)) : n;
;       if (FP8) {
;         float f[8];
; #pragma unroll
;         for (int j = 0; j < 8; ++j) f[j] = tile[(c * 8 + j) * 65 + ns] * wscale;
;         u32x2 o = {pk4_fp8(f[0], f[1], f[2], f[3]), pk4_fp8(f[4], f[5], f[6], f[7])};
;         *(u32x2*)((unsigned char*)Wt + (size_t)(n0 + n) * K + k0 + c * 8) = o;
;       } else {
;         u32x4 o;
; #pragma unroll
;         for (int j = 0; j < 4; ++j) o[j] = pk2(tile[(c * 8 + 2 * j) * 65 + ns], tile[(c * 8 + 2 * j + 1) * 65 + ns]);
;         *(u32x4*)(Wt + (size_t)(n0 + n) * K + k0 + c * 8) = o;
;       }
;     }
.Lcw0_top:
	s_mov_b32 s100, s13
	s_mov_b32 s101, s12
	s_mul_hi_i32 s10, s100, 0x2aaaaaab
	s_lshr_b32 s11, s10, 31
	s_ashr_i32 s10, s10, 3
	s_add_i32 s10, s10, s11
	s_lshl_b32 s14, s10, 6
	s_mul_i32 s15, s10, 0xfffff400
	v_or_b32_e32 v10, s14, v12
	s_movk_i32 s10, 0x800
	v_cmp_gt_i32_e32 vcc, s10, v10
	v_mov_b32_e32 v98, 0
	v_mov_b32_e32 v99, 0
	v_mov_b32_e32 v100, 0
	v_mov_b32_e32 v101, 0
	v_mov_b32_e32 v102, 0
	v_mov_b32_e32 v103, 0
	v_mov_b32_e32 v104, 0
	v_mov_b32_e32 v105, 0
	s_and_saveexec_b64 s[10:11], vcc
	s_add_i32 s16, s15, s101
	v_add_u32_e32 v118, s16, v14
	v_add_u32_e32 v122, s16, v15
	v_ashrrev_i32_e32 v11, 31, v10
	v_ashrrev_i32_e32 v119, 31, v118
	v_ashrrev_i32_e32 v123, 31, v122
	v_lshl_add_u64 v[116:117], v[10:11], 2, s[0:1]
	v_lshlrev_b64 v[118:119], 13, v[118:119]
	v_lshlrev_b64 v[122:123], 13, v[122:123]
	v_lshl_add_u64 v[118:119], v[116:117], 0, v[118:119]
	v_lshl_add_u64 v[116:117], v[116:117], 0, v[122:123]
	global_load_dwordx4 v[98:101], v[118:119], off
	s_nop 0
	global_load_dwordx4 v[102:105], v[116:117], off
	s_or_b64 exec, exec, s[10:11]
	s_add_i32 s100, s100, s33
	s_add_i32 s101, s101, s92
	s_cmpk_lt_i32 s100, 0x600
	s_cselect_b32 s100, s100, s13
	s_cselect_b32 s101, s101, s12
	s_mul_hi_i32 s10, s100, 0x2aaaaaab
	s_lshr_b32 s11, s10, 31
	s_ashr_i32 s10, s10, 3
	s_add_i32 s10, s10, s11
	s_lshl_b32 s14, s10, 6
	s_mul_i32 s15, s10, 0xfffff400
	v_or_b32_e32 v10, s14, v12
	s_movk_i32 s10, 0x800
	v_cmp_gt_i32_e32 vcc, s10, v10
	v_mov_b32_e32 v106, 0
	v_mov_b32_e32 v107, 0
	v_mov_b32_e32 v108, 0
	v_mov_b32_e32 v109, 0
	v_mov_b32_e32 v110, 0
	v_mov_b32_e32 v111, 0
	v_mov_b32_e32 v112, 0
	v_mov_b32_e32 v113, 0
	s_and_saveexec_b64 s[10:11], vcc
	s_add_i32 s16, s15, s101
	v_add_u32_e32 v118, s16, v14
	v_add_u32_e32 v122, s16, v15
	v_ashrrev_i32_e32 v11, 31, v10
	v_ashrrev_i32_e32 v119, 31, v118
	v_ashrrev_i32_e32 v123, 31, v122
	v_lshl_add_u64 v[116:117], v[10:11], 2, s[0:1]
	v_lshlrev_b64 v[118:119], 13, v[118:119]
	v_lshlrev_b64 v[122:123], 13, v[122:123]
	v_lshl_add_u64 v[118:119], v[116:117], 0, v[118:119]
	v_lshl_add_u64 v[116:117], v[116:117], 0, v[122:123]
	global_load_dwordx4 v[106:109], v[118:119], off
	s_nop 0
	global_load_dwordx4 v[110:113], v[116:117], off
	s_or_b64 exec, exec, s[10:11]
	s_add_i32 s100, s100, s33
	s_add_i32 s101, s101, s92
	s_cmpk_lt_i32 s100, 0x600
	s_cselect_b32 s100, s100, s13
	s_cselect_b32 s101, s101, s12
	s_mul_hi_i32 s10, s100, 0x2aaaaaab
	s_lshr_b32 s11, s10, 31
	s_ashr_i32 s10, s10, 3
	s_add_i32 s10, s10, s11
	s_lshl_b32 s14, s10, 6
	s_mul_i32 s15, s10, 0xfffff400
	v_or_b32_e32 v10, s14, v12
	s_movk_i32 s10, 0x800
	v_cmp_gt_i32_e32 vcc, s10, v10
	v_mov_b32_e32 v208, 0
	v_mov_b32_e32 v209, 0
	v_mov_b32_e32 v210, 0
	v_mov_b32_e32 v211, 0
	v_mov_b32_e32 v212, 0
	v_mov_b32_e32 v213, 0
	v_mov_b32_e32 v214, 0
	v_mov_b32_e32 v215, 0
	s_and_saveexec_b64 s[10:11], vcc
	s_add_i32 s16, s15, s101
	v_add_u32_e32 v118, s16, v14
	v_add_u32_e32 v122, s16, v15
	v_ashrrev_i32_e32 v11, 31, v10
	v_ashrrev_i32_e32 v119, 31, v118
	v_ashrrev_i32_e32 v123, 31, v122
	v_lshl_add_u64 v[116:117], v[10:11], 2, s[0:1]
	v_lshlrev_b64 v[118:119], 13, v[118:119]
	v_lshlrev_b64 v[122:123], 13, v[122:123]
	v_lshl_add_u64 v[118:119], v[116:117], 0, v[118:119]
	v_lshl_add_u64 v[116:117], v[116:117], 0, v[122:123]
	global_load_dwordx4 v[208:211], v[118:119], off
	s_nop 0
	global_load_dwordx4 v[212:215], v[116:117], off
	s_or_b64 exec, exec, s[10:11]
	s_mul_hi_i32 s10, s13, 0x2aaaaaab
	s_lshr_b32 s11, s10, 31
	s_ashr_i32 s10, s10, 3
	s_add_i32 s10, s10, s11
	s_lshl_b32 s14, s10, 6
	s_mul_i32 s15, s10, 0xfffff400
	v_or_b32_e32 v10, s14, v12
	s_movk_i32 s10, 0x800
	v_cmp_gt_i32_e32 vcc, s10, v10
	s_waitcnt lgkmcnt(0)
	s_barrier
	s_waitcnt vmcnt(4)
	ds_write2_b32 v16, v98, v99 offset1:1
	ds_write2_b32 v16, v100, v101 offset0:2 offset1:3
	ds_write2_b32 v17, v102, v103 offset1:1
	ds_write2_b32 v17, v104, v105 offset0:2 offset1:3
	s_waitcnt lgkmcnt(0)
	s_barrier
	ds_read2_b32 v[2:3], v18 offset1:65
	ds_read2_b32 v[4:5], v18 offset0:130 offset1:195
	s_add_i32 s10, s12, s15
	s_ashr_i32 s11, s10, 31
	s_add_i32 s13, s13, s33
	s_waitcnt lgkmcnt(1)
	v_mul_f32_e32 v8, 0x43800000, v2
	v_add_u32_e32 v2, 0x400, v18
	ds_read2_b32 v[6:7], v2 offset0:4 offset1:69
	v_mul_f32_e32 v9, 0x43800000, v3
	ds_read2_b32 v[2:3], v2 offset0:134 offset1:199
	s_waitcnt lgkmcnt(2)
	v_mul_f32_e32 v4, 0x43800000, v4
	v_mul_f32_e32 v5, 0x43800000, v5
	s_waitcnt lgkmcnt(1)
	v_mul_f32_e32 v6, 0x43800000, v6
	v_mul_f32_e32 v7, 0x43800000, v7
	s_waitcnt lgkmcnt(0)
	v_mul_f32_e32 v10, 0x43800000, v2
	v_mul_f32_e32 v11, 0x43800000, v3
	v_med3_f32 v3, v8, s93, v223
	v_med3_f32 v8, v9, s93, v223
	v_mov_b32_e32 v2, v1
	v_cvt_pk_fp8_f32 v2, v3, v8
	v_med3_f32 v6, v6, s93, v223
	v_med3_f32 v7, v7, s93, v223
	v_mov_b32_e32 v3, v1
	v_cvt_pk_fp8_f32 v3, v6, v7
	v_med3_f32 v4, v4, s93, v223
	v_med3_f32 v5, v5, s93, v223
	v_cvt_pk_fp8_f32 v2, v4, v5 op_sel:[0,0,1]
	v_med3_f32 v4, v10, s93, v223
	v_med3_f32 v5, v11, s93, v223
	v_cvt_pk_fp8_f32 v3, v4, v5 op_sel:[0,0,1]
	v_add_u32_e32 v6, s14, v13
	v_mov_b64_e32 v[4:5], s[18:19]
	v_mad_i64_i32 v[4:5], s[14:15], v6, s34, v[4:5]
	v_lshl_add_u64 v[4:5], v[4:5], 0, s[10:11]
	s_add_i32 s12, s12, s92
	v_lshl_add_u64 v[4:5], v[4:5], 0, v[0:1]
	s_cmpk_lt_i32 s13, 0x600
	global_store_dwordx2 v[4:5], v[2:3], off
	s_cbranch_scc0 .Lcw0_x1
;     ...
;   for (int t = blockIdx.x; t < ntk * ntn; t += gridDim.x) {
;     const int tk = t % ntk, tn = t / ntk, k0 = tk * 64, n0 = tn * 64;
;     __syncthreads();
; #pragma unroll
;     for (int i = 0; i < 2; ++i) {
;       const int id = tid + 512 * i, kr = id >> 4, n4 = (id & 15) * 4;
;       f32x4 v = {0.f, 0.f, 0.f, 0.f};
;       const int nd = n0 + n4, nsrc = (nvalid < 0) ? nd : (nd < csplit ? nd + coff1 : nd + coff2);
;       if (nd < ((nvalid < 0) ? N : nvalid)) v = *(const f32x4*)(W + (size_t)(k0 + kr) * N + nsrc);
;       tile[kr * 65 + n4 + 0] = v[0]; tile[kr * 65 + n4 + 1] = v[1]; tile[kr * 65 + n4 + 2] = v[2]; tile[kr * 65 + n4 + 3] = v[3];
;     }
;     __syncthreads();
;     {
;       const int n = tid >> 3, c = tid & 7;
;       bool rot = false;
;       if (PERM == 1) rot = (n0 == rot_n0);
;       if (PERM == 2) rot = ((tn % 3) == 2);
;       const int ns = rot ? ((n >> 1) + 32 * (n & 1)) : n;
;       if (FP8) {
;         float f[8];
; #pragma unroll
;         for (int j = 0; j < 8; ++j) f[j] = tile[(c * 8 + j) * 65 + ns] * wscale;
;         u32x2 o = {pk4_fp8(f[0], f[1], f[2], f[3]), pk4_fp8(f[4], f[5], f[6], f[7])};
;         *(u32x2*)((unsigned char*)Wt + (size_t)(n0 + n) * K + k0 + c * 8) = o;
;       } else {
;         u32x4 o;
; #pragma unroll
;         for (int j = 0; j < 4; ++j) o[j] = pk2(tile[(c * 8 + 2 * j) * 65 + ns], tile[(c * 8 + 2 * j + 1) * 65 + ns]);
;         *(u32x4*)(Wt + (size_t)(n0 + n) * K + k0 + c * 8) = o;
;       }
;     }
	s_mul_hi_i32 s10, s13, 0x2aaaaaab
	s_lshr_b32 s11, s10, 31
	s_ashr_i32 s10, s10, 3
	s_add_i32 s10, s10, s11
	s_lshl_b32 s14, s10, 6
	s_mul_i32 s15, s10, 0xfffff400
	v_or_b32_e32 v10, s14, v12
	s_movk_i32 s10, 0x800
	v_cmp_gt_i32_e32 vcc, s10, v10
	s_waitcnt lgkmcnt(0)
	s_barrier
	s_waitcnt vmcnt(3)
	ds_write2_b32 v16, v106, v107 offset1:1
	ds_write2_b32 v16, v108, v109 offset0:2 offset1:3
	ds_write2_b32 v17, v110, v111 offset1:1
	ds_write2_b32 v17, v112, v113 offset0:2 offset1:3
	s_waitcnt lgkmcnt(0)
	s_barrier
	ds_read2_b32 v[2:3], v18 offset1:65
	ds_read2_b32 v[4:5], v18 offset0:130 offset1:195
	s_add_i32 s10, s12, s15
	s_ashr_i32 s11, s10, 31
	s_add_i32 s13, s13, s33
	s_waitcnt lgkmcnt(1)
	v_mul_f32_e32 v8, 0x43800000, v2
	v_add_u32_e32 v2, 0x400, v18
	ds_read2_b32 v[6:7], v2 offset0:4 offset1:69
	v_mul_f32_e32 v9, 0x43800000, v3
	ds_read2_b32 v[2:3], v2 offset0:134 offset1:199
	s_waitcnt lgkmcnt(2)
	v_mul_f32_e32 v4, 0x43800000, v4
	v_mul_f32_e32 v5, 0x43800000, v5
	s_waitcnt lgkmcnt(1)
	v_mul_f32_e32 v6, 0x43800000, v6
	v_mul_f32_e32 v7, 0x43800000, v7
	s_waitcnt lgkmcnt(0)
	v_mul_f32_e32 v10, 0x43800000, v2
	v_mul_f32_e32 v11, 0x43800000, v3
	v_med3_f32 v3, v8, s93, v223
	v_med3_f32 v8, v9, s93, v223
	v_mov_b32_e32 v2, v1
	v_cvt_pk_fp8_f32 v2, v3, v8
	v_med3_f32 v6, v6, s93, v223
	v_med3_f32 v7, v7, s93, v223
	v_mov_b32_e32 v3, v1
	v_cvt_pk_fp8_f32 v3, v6, v7
	v_med3_f32 v4, v4, s93, v223
	v_med3_f32 v5, v5, s93, v223
	v_cvt_pk_fp8_f32 v2, v4, v5 op_sel:[0,0,1]
	v_med3_f32 v4, v10, s93, v223
	v_med3_f32 v5, v11, s93, v223
	v_cvt_pk_fp8_f32 v3, v4, v5 op_sel:[0,0,1]
	v_add_u32_e32 v6, s14, v13
	v_mov_b64_e32 v[4:5], s[18:19]
	v_mad_i64_i32 v[4:5], s[14:15], v6, s34, v[4:5]
	v_lshl_add_u64 v[4:5], v[4:5], 0, s[10:11]
	s_add_i32 s12, s12, s92
	v_lshl_add_u64 v[4:5], v[4:5], 0, v[0:1]
	s_cmpk_lt_i32 s13, 0x600
	global_store_dwordx2 v[4:5], v[2:3], off
	s_cbranch_scc0 .Lcw0_x2
	s_mul_hi_i32 s10, s13, 0x2aaaaaab
	s_lshr_b32 s11, s10, 31
	s_ashr_i32 s10, s10, 3
	s_add_i32 s10, s10, s11
	s_lshl_b32 s14, s10, 6
	s_mul_i32 s15, s10, 0xfffff400
	v_or_b32_e32 v10, s14, v12
	s_movk_i32 s10, 0x800
	v_cmp_gt_i32_e32 vcc, s10, v10
	s_waitcnt lgkmcnt(0)
	s_barrier
	s_waitcnt vmcnt(2)
	ds_write2_b32 v16, v208, v209 offset1:1
	ds_write2_b32 v16, v210, v211 offset0:2 offset1:3
	ds_write2_b32 v17, v212, v213 offset1:1
	ds_write2_b32 v17, v214, v215 offset0:2 offset1:3
	s_waitcnt lgkmcnt(0)
	s_barrier
	ds_read2_b32 v[2:3], v18 offset1:65
	ds_read2_b32 v[4:5], v18 offset0:130 offset1:195
	s_add_i32 s10, s12, s15
	s_ashr_i32 s11, s10, 31
	s_add_i32 s13, s13, s33
	s_waitcnt lgkmcnt(1)
	v_mul_f32_e32 v8, 0x43800000, v2
	v_add_u32_e32 v2, 0x400, v18
	ds_read2_b32 v[6:7], v2 offset0:4 offset1:69
	v_mul_f32_e32 v9, 0x43800000, v3
	ds_read2_b32 v[2:3], v2 offset0:134 offset1:199
	s_waitcnt lgkmcnt(2)
	v_mul_f32_e32 v4, 0x43800000, v4
	v_mul_f32_e32 v5, 0x43800000, v5
	s_waitcnt lgkmcnt(1)
	v_mul_f32_e32 v6, 0x43800000, v6
	v_mul_f32_e32 v7, 0x43800000, v7
	s_waitcnt lgkmcnt(0)
	v_mul_f32_e32 v10, 0x43800000, v2
	v_mul_f32_e32 v11, 0x43800000, v3
	v_med3_f32 v3, v8, s93, v223
	v_med3_f32 v8, v9, s93, v223
	v_mov_b32_e32 v2, v1
	v_cvt_pk_fp8_f32 v2, v3, v8
	v_med3_f32 v6, v6, s93, v223
	v_med3_f32 v7, v7, s93, v223
	v_mov_b32_e32 v3, v1
	v_cvt_pk_fp8_f32 v3, v6, v7
	v_med3_f32 v4, v4, s93, v223
	v_med3_f32 v5, v5, s93, v223
	v_cvt_pk_fp8_f32 v2, v4, v5 op_sel:[0,0,1]
	v_med3_f32 v4, v10, s93, v223
	v_med3_f32 v5, v11, s93, v223
	v_cvt_pk_fp8_f32 v3, v4, v5 op_sel:[0,0,1]
	v_add_u32_e32 v6, s14, v13
	v_mov_b64_e32 v[4:5], s[18:19]
	v_mad_i64_i32 v[4:5], s[14:15], v6, s34, v[4:5]
	v_lshl_add_u64 v[4:5], v[4:5], 0, s[10:11]
	s_add_i32 s12, s12, s92
	v_lshl_add_u64 v[4:5], v[4:5], 0, v[0:1]
	s_cmpk_lt_i32 s13, 0x600
	global_store_dwordx2 v[4:5], v[2:3], off
	s_cbranch_scc0 .LBB0_1425
	s_branch .Lcw0_top
.Lcw0_x1:
	s_waitcnt vmcnt(1)
	s_branch .LBB0_1425
.Lcw0_x2:
	s_waitcnt vmcnt(2)
	s_branch .LBB0_1425

;     ...
;   for (int t = blockIdx.x; t < ntk * ntn; t += gridDim.x) {
;     const int tk = t % ntk, tn = t / ntk, k0 = tk * 64, n0 = tn * 64;
;     __syncthreads();
; #pragma unroll
;     for (int i = 0; i < 2; ++i) {
;       const int id = tid + 512 * i, kr = id >> 4, n4 = (id & 15) * 4;
;       f32x4 v = {0.f, 0.f, 0.f, 0.f};
;       const int nd = n0 + n4, nsrc = (nvalid < 0) ? nd : (nd < csplit ? nd + coff1 : nd + coff2);
;       if (nd < ((nvalid < 0) ? N : nvalid)) v = *(const f32x4*)(W + (size_t)(k0 + kr) * N + nsrc);
;       tile[kr * 65 + n4 + 0] = v[0]; tile[kr * 65 + n4 + 1] = v[1]; tile[kr * 65 + n4 + 2] = v[2]; tile[kr * 65 + n4 + 3] = v[3];
;     }
;     __syncthreads();
;     {
;       const int n = tid >> 3, c = tid & 7;
;       bool rot = false;
;       if (PERM == 1) rot = (n0 == rot_n0);
;       if (PERM == 2) rot = ((tn % 3) == 2);
;       const int ns = rot ? ((n >> 1) + 32 * (n & 1)) : n;
;       if (FP8) {
;         float f[8];
; #pragma unroll
;         for (int j = 0; j < 8; ++j) f[j] = tile[(c * 8 + j) * 65 + ns] * wscale;
;         u32x2 o = {pk4_fp8(f[0], f[1], f[2], f[3]), pk4_fp8(f[4], f[5], f[6], f[7])};
;         *(u32x2*)((unsigned char*)Wt + (size_t)(n0 + n) * K + k0 + c * 8) = o;
;       } else {
;         u32x4 o;
; #pragma unroll
;         for (int j = 0; j < 4; ++j) o[j] = pk2(tile[(c * 8 + 2 * j) * 65 + ns], tile[(c * 8 + 2 * j + 1) * 65 + ns]);
;         *(u32x4*)(Wt + (size_t)(n0 + n) * K + k0 + c * 8) = o;
;       }
;     }
.Lcw1_top:
	s_mov_b32 s100, s13
	s_mov_b32 s101, s12
	s_ashr_i32 s10, s100, 31
	s_lshr_b32 s10, s10, 27
	s_add_i32 s10, s100, s10
	s_ashr_i32 s10, s10, 5
	s_lshl_b32 s15, s10, 6
	s_lshl_b32 s11, s10, 11
	v_or_b32_e32 v18, s15, v10
	s_movk_i32 s10, 0x1250
	s_sub_i32 s16, 0, s11
	v_cmp_gt_i32_e32 vcc, s10, v18
	v_mov_b32_e32 v98, 0
	v_mov_b32_e32 v99, 0
	v_mov_b32_e32 v100, 0
	v_mov_b32_e32 v101, 0
	v_mov_b32_e32 v102, 0
	v_mov_b32_e32 v103, 0
	v_mov_b32_e32 v104, 0
	v_mov_b32_e32 v105, 0
	s_and_saveexec_b64 s[10:11], vcc
	s_movk_i32 s17, 0x650
	v_cmp_gt_i32_e32 vcc, s17, v18
	v_mov_b32_e32 v116, 0xc00
	v_readlane_b32 s36, v250, 26
	v_cndmask_b32_e32 v116, v116, v235, vcc
	s_add_i32 s17, s16, s101
	v_readlane_b32 s42, v250, 32
	v_readlane_b32 s43, v250, 33
	v_add_u32_e32 v116, v116, v18
	v_add_u32_e32 v117, s17, v13
	v_mov_b64_e32 v[118:119], s[42:43]
	s_movk_i32 s23, 0x7940
	v_mad_i64_i32 v[122:123], s[18:19], v117, s23, v[118:119]
	v_ashrrev_i32_e32 v117, 31, v116
	v_add_u32_e32 v124, s17, v14
	v_lshlrev_b64 v[116:117], 2, v[116:117]
	v_mad_i64_i32 v[118:119], s[18:19], v124, s23, v[118:119]
	v_lshl_add_u64 v[122:123], v[122:123], 0, v[116:117]
	v_lshl_add_u64 v[116:117], v[118:119], 0, v[116:117]
	global_load_dwordx4 v[98:101], v[122:123], off
	s_nop 0
	global_load_dwordx4 v[102:105], v[116:117], off
	v_readlane_b32 s42, v254, 30
	v_readlane_b32 s37, v250, 27
	v_readlane_b32 s38, v250, 28
	v_readlane_b32 s39, v250, 29
	v_readlane_b32 s40, v250, 30
	v_readlane_b32 s41, v250, 31
	v_readlane_b32 s44, v250, 34
	v_readlane_b32 s45, v250, 35
	v_readlane_b32 s46, v250, 36
	v_readlane_b32 s47, v250, 37
	v_readlane_b32 s48, v250, 38
	v_readlane_b32 s49, v250, 39
	v_readlane_b32 s50, v250, 40
	v_readlane_b32 s51, v250, 41
	v_readlane_b32 s43, v254, 31
	s_or_b64 exec, exec, s[10:11]
	s_add_i32 s100, s100, s33
	s_add_i32 s101, s101, s92
	s_cmpk_lt_i32 s100, 0x980
	s_cselect_b32 s100, s100, s13
	s_cselect_b32 s101, s101, s12
	s_ashr_i32 s10, s100, 31
	s_lshr_b32 s10, s10, 27
	s_add_i32 s10, s100, s10
	s_ashr_i32 s10, s10, 5
	s_lshl_b32 s15, s10, 6
	s_lshl_b32 s11, s10, 11
	v_or_b32_e32 v18, s15, v10
	s_movk_i32 s10, 0x1250
	s_sub_i32 s16, 0, s11
	v_cmp_gt_i32_e32 vcc, s10, v18
	v_mov_b32_e32 v106, 0
	v_mov_b32_e32 v107, 0
	v_mov_b32_e32 v108, 0
	v_mov_b32_e32 v109, 0
	v_mov_b32_e32 v110, 0
	v_mov_b32_e32 v111, 0
	v_mov_b32_e32 v112, 0
	v_mov_b32_e32 v113, 0
	s_and_saveexec_b64 s[10:11], vcc
	s_movk_i32 s17, 0x650
	v_cmp_gt_i32_e32 vcc, s17, v18
	v_mov_b32_e32 v116, 0xc00
	v_readlane_b32 s36, v250, 26
	v_cndmask_b32_e32 v116, v116, v235, vcc
	s_add_i32 s17, s16, s101
	v_readlane_b32 s42, v250, 32
	v_readlane_b32 s43, v250, 33
	v_add_u32_e32 v116, v116, v18
	v_add_u32_e32 v117, s17, v13
	v_mov_b64_e32 v[118:119], s[42:43]
	s_movk_i32 s23, 0x7940
	v_mad_i64_i32 v[122:123], s[18:19], v117, s23, v[118:119]
	v_ashrrev_i32_e32 v117, 31, v116
	v_add_u32_e32 v124, s17, v14
	v_lshlrev_b64 v[116:117], 2, v[116:117]
	v_mad_i64_i32 v[118:119], s[18:19], v124, s23, v[118:119]
	v_lshl_add_u64 v[122:123], v[122:123], 0, v[116:117]
	v_lshl_add_u64 v[116:117], v[118:119], 0, v[116:117]
	global_load_dwordx4 v[106:109], v[122:123], off
	s_nop 0
	global_load_dwordx4 v[110:113], v[116:117], off
	v_readlane_b32 s42, v254, 30
	v_readlane_b32 s37, v250, 27
	v_readlane_b32 s38, v250, 28
	v_readlane_b32 s39, v250, 29
	v_readlane_b32 s40, v250, 30
	v_readlane_b32 s41, v250, 31
	v_readlane_b32 s44, v250, 34
	v_readlane_b32 s45, v250, 35
	v_readlane_b32 s46, v250, 36
	v_readlane_b32 s47, v250, 37
	v_readlane_b32 s48, v250, 38
	v_readlane_b32 s49, v250, 39
	v_readlane_b32 s50, v250, 40
	v_readlane_b32 s51, v250, 41
	v_readlane_b32 s43, v254, 31
	s_or_b64 exec, exec, s[10:11]
	s_add_i32 s100, s100, s33
	s_add_i32 s101, s101, s92
	s_cmpk_lt_i32 s100, 0x980
	s_cselect_b32 s100, s100, s13
	s_cselect_b32 s101, s101, s12
	s_ashr_i32 s10, s100, 31
	s_lshr_b32 s10, s10, 27
	s_add_i32 s10, s100, s10
	s_ashr_i32 s10, s10, 5
	s_lshl_b32 s15, s10, 6
	s_lshl_b32 s11, s10, 11
	v_or_b32_e32 v18, s15, v10
	s_movk_i32 s10, 0x1250
	s_sub_i32 s16, 0, s11
	v_cmp_gt_i32_e32 vcc, s10, v18
	v_mov_b32_e32 v208, 0
	v_mov_b32_e32 v209, 0
	v_mov_b32_e32 v210, 0
	v_mov_b32_e32 v211, 0
	v_mov_b32_e32 v212, 0
	v_mov_b32_e32 v213, 0
	v_mov_b32_e32 v214, 0
	v_mov_b32_e32 v215, 0
	s_and_saveexec_b64 s[10:11], vcc
	s_movk_i32 s17, 0x650
	v_cmp_gt_i32_e32 vcc, s17, v18
	v_mov_b32_e32 v116, 0xc00
	v_readlane_b32 s36, v250, 26
	v_cndmask_b32_e32 v116, v116, v235, vcc
	s_add_i32 s17, s16, s101
	v_readlane_b32 s42, v250, 32
	v_readlane_b32 s43, v250, 33
	v_add_u32_e32 v116, v116, v18
	v_add_u32_e32 v117, s17, v13
	v_mov_b64_e32 v[118:119], s[42:43]
	s_movk_i32 s23, 0x7940
	v_mad_i64_i32 v[122:123], s[18:19], v117, s23, v[118:119]
	v_ashrrev_i32_e32 v117, 31, v116
	v_add_u32_e32 v124, s17, v14
	v_lshlrev_b64 v[116:117], 2, v[116:117]
	v_mad_i64_i32 v[118:119], s[18:19], v124, s23, v[118:119]
	v_lshl_add_u64 v[122:123], v[122:123], 0, v[116:117]
	v_lshl_add_u64 v[116:117], v[118:119], 0, v[116:117]
	global_load_dwordx4 v[208:211], v[122:123], off
	s_nop 0
	global_load_dwordx4 v[212:215], v[116:117], off
	v_readlane_b32 s42, v254, 30
	v_readlane_b32 s37, v250, 27
	v_readlane_b32 s38, v250, 28
	v_readlane_b32 s39, v250, 29
	v_readlane_b32 s40, v250, 30
	v_readlane_b32 s41, v250, 31
	v_readlane_b32 s44, v250, 34
	v_readlane_b32 s45, v250, 35
	v_readlane_b32 s46, v250, 36
	v_readlane_b32 s47, v250, 37
	v_readlane_b32 s48, v250, 38
	v_readlane_b32 s49, v250, 39
	v_readlane_b32 s50, v250, 40
	v_readlane_b32 s51, v250, 41
	v_readlane_b32 s43, v254, 31
	s_or_b64 exec, exec, s[10:11]
	s_ashr_i32 s10, s13, 31
	s_lshr_b32 s10, s10, 27
	s_add_i32 s10, s13, s10
	s_ashr_i32 s10, s10, 5
	s_lshl_b32 s15, s10, 6
	s_lshl_b32 s11, s10, 11
	v_or_b32_e32 v18, s15, v10
	s_movk_i32 s10, 0x1250
	s_sub_i32 s16, 0, s11
	v_cmp_gt_i32_e32 vcc, s10, v18
	s_waitcnt lgkmcnt(0)
	s_barrier
;     ...
;   for (int t = blockIdx.x; t < ntk * ntn; t += gridDim.x) {
;     const int tk = t % ntk, tn = t / ntk, k0 = tk * 64, n0 = tn * 64;
;     __syncthreads();
; #pragma unroll
;     for (int i = 0; i < 2; ++i) {
;       const int id = tid + 512 * i, kr = id >> 4, n4 = (id & 15) * 4;
;       f32x4 v = {0.f, 0.f, 0.f, 0.f};
;       const int nd = n0 + n4, nsrc = (nvalid < 0) ? nd : (nd < csplit ? nd + coff1 : nd + coff2);
;       if (nd < ((nvalid < 0) ? N : nvalid)) v = *(const f32x4*)(W + (size_t)(k0 + kr) * N + nsrc);
;       tile[kr * 65 + n4 + 0] = v[0]; tile[kr * 65 + n4 + 1] = v[1]; tile[kr * 65 + n4 + 2] = v[2]; tile[kr * 65 + n4 + 3] = v[3];
;     }
;     __syncthreads();
;     {
;       const int n = tid >> 3, c = tid & 7;
;       bool rot = false;
;       if (PERM == 1) rot = (n0 == rot_n0);
;       if (PERM == 2) rot = ((tn % 3) == 2);
;       const int ns = rot ? ((n >> 1) + 32 * (n & 1)) : n;
;       if (FP8) {
;         float f[8];
; #pragma unroll
;         for (int j = 0; j < 8; ++j) f[j] = tile[(c * 8 + j) * 65 + ns] * wscale;
;         u32x2 o = {pk4_fp8(f[0], f[1], f[2], f[3]), pk4_fp8(f[4], f[5], f[6], f[7])};
;         *(u32x2*)((unsigned char*)Wt + (size_t)(n0 + n) * K + k0 + c * 8) = o;
;       } else {
;         u32x4 o;
; #pragma unroll
;         for (int j = 0; j < 4; ++j) o[j] = pk2(tile[(c * 8 + 2 * j) * 65 + ns], tile[(c * 8 + 2 * j + 1) * 65 + ns]);
;         *(u32x4*)(Wt + (size_t)(n0 + n) * K + k0 + c * 8) = o;
;       }
;     }
	s_waitcnt vmcnt(4)
	ds_write2_b32 v16, v98, v99 offset1:1
	ds_write2_b32 v16, v100, v101 offset0:2 offset1:3
	ds_write2_b32 v17, v102, v103 offset1:1
	ds_write2_b32 v17, v104, v105 offset0:2 offset1:3
	s_waitcnt lgkmcnt(0)
	s_barrier
	ds_read2_b32 v[2:3], v12 offset1:130
	ds_read2_b32 v[4:5], v15 offset0:65 offset1:195
	v_add_u32_e32 v6, 0x400, v15
	ds_read2_b32 v[6:7], v6 offset0:69 offset1:199
	s_add_i32 s10, s12, s16
	v_readlane_b32 s16, v253, 15
	s_waitcnt lgkmcnt(1)
	v_cvt_pk_bf16_f32 v2, v2, v4
	v_add_u32_e32 v4, 0x400, v12
	v_cvt_pk_bf16_f32 v3, v3, v5
	ds_read2_b32 v[4:5], v4 offset0:4 offset1:134
	v_readlane_b32 s17, v253, 16
	s_ashr_i32 s11, s10, 31
	s_add_i32 s13, s13, s33
	s_add_i32 s12, s12, s92
	s_waitcnt lgkmcnt(0)
	v_cvt_pk_bf16_f32 v4, v4, v6
	v_add_u32_e32 v6, s15, v11
	v_cvt_pk_bf16_f32 v5, v5, v7
	v_ashrrev_i32_e32 v7, 31, v6
	v_lshlrev_b64 v[6:7], 12, v[6:7]
	v_lshl_add_u64 v[6:7], s[16:17], 0, v[6:7]
	v_lshl_add_u64 v[6:7], s[10:11], 1, v[6:7]
	v_lshl_add_u64 v[6:7], v[6:7], 0, v[0:1]
	s_cmpk_lt_i32 s13, 0x980
	global_store_dwordx4 v[6:7], v[2:5], off
	s_cbranch_scc0 .Lcw1_x1
	s_ashr_i32 s10, s13, 31
	s_lshr_b32 s10, s10, 27
	s_add_i32 s10, s13, s10
	s_ashr_i32 s10, s10, 5
	s_lshl_b32 s15, s10, 6
	s_lshl_b32 s11, s10, 11
	v_or_b32_e32 v18, s15, v10
	s_movk_i32 s10, 0x1250
	s_sub_i32 s16, 0, s11
	v_cmp_gt_i32_e32 vcc, s10, v18
	s_waitcnt lgkmcnt(0)
	s_barrier
	s_waitcnt vmcnt(3)
	ds_write2_b32 v16, v106, v107 offset1:1
	ds_write2_b32 v16, v108, v109 offset0:2 offset1:3
	ds_write2_b32 v17, v110, v111 offset1:1
	ds_write2_b32 v17, v112, v113 offset0:2 offset1:3
	s_waitcnt lgkmcnt(0)
	s_barrier
	ds_read2_b32 v[2:3], v12 offset1:130
	ds_read2_b32 v[4:5], v15 offset0:65 offset1:195
	v_add_u32_e32 v6, 0x400, v15
	ds_read2_b32 v[6:7], v6 offset0:69 offset1:199
	s_add_i32 s10, s12, s16
	v_readlane_b32 s16, v253, 15
	s_waitcnt lgkmcnt(1)
	v_cvt_pk_bf16_f32 v2, v2, v4
	v_add_u32_e32 v4, 0x400, v12
	v_cvt_pk_bf16_f32 v3, v3, v5
	ds_read2_b32 v[4:5], v4 offset0:4 offset1:134
	v_readlane_b32 s17, v253, 16
	s_ashr_i32 s11, s10, 31
	s_add_i32 s13, s13, s33
	s_add_i32 s12, s12, s92
	s_waitcnt lgkmcnt(0)
	v_cvt_pk_bf16_f32 v4, v4, v6
	v_add_u32_e32 v6, s15, v11
	v_cvt_pk_bf16_f32 v5, v5, v7
	v_ashrrev_i32_e32 v7, 31, v6
	v_lshlrev_b64 v[6:7], 12, v[6:7]
	v_lshl_add_u64 v[6:7], s[16:17], 0, v[6:7]
	v_lshl_add_u64 v[6:7], s[10:11], 1, v[6:7]
	v_lshl_add_u64 v[6:7], v[6:7], 0, v[0:1]
	s_cmpk_lt_i32 s13, 0x980
	global_store_dwordx4 v[6:7], v[2:5], off
	s_cbranch_scc0 .Lcw1_x2
	s_ashr_i32 s10, s13, 31
	s_lshr_b32 s10, s10, 27
	s_add_i32 s10, s13, s10
	s_ashr_i32 s10, s10, 5
	s_lshl_b32 s15, s10, 6
	s_lshl_b32 s11, s10, 11
	v_or_b32_e32 v18, s15, v10
	s_movk_i32 s10, 0x1250
	s_sub_i32 s16, 0, s11
	v_cmp_gt_i32_e32 vcc, s10, v18
	s_waitcnt lgkmcnt(0)
	s_barrier
	s_waitcnt vmcnt(2)
	ds_write2_b32 v16, v208, v209 offset1:1
	ds_write2_b32 v16, v210, v211 offset0:2 offset1:3
	ds_write2_b32 v17, v212, v213 offset1:1
	ds_write2_b32 v17, v214, v215 offset0:2 offset1:3
	s_waitcnt lgkmcnt(0)
	s_barrier
	ds_read2_b32 v[2:3], v12 offset1:130
	ds_read2_b32 v[4:5], v15 offset0:65 offset1:195
	v_add_u32_e32 v6, 0x400, v15
	ds_read2_b32 v[6:7], v6 offset0:69 offset1:199
	s_add_i32 s10, s12, s16
	v_readlane_b32 s16, v253, 15
	s_waitcnt lgkmcnt(1)
	v_cvt_pk_bf16_f32 v2, v2, v4
	v_add_u32_e32 v4, 0x400, v12
	v_cvt_pk_bf16_f32 v3, v3, v5
	ds_read2_b32 v[4:5], v4 offset0:4 offset1:134
	v_readlane_b32 s17, v253, 16
	s_ashr_i32 s11, s10, 31
	s_add_i32 s13, s13, s33
	s_add_i32 s12, s12, s92
	s_waitcnt lgkmcnt(0)
	v_cvt_pk_bf16_f32 v4, v4, v6
	v_add_u32_e32 v6, s15, v11
	v_cvt_pk_bf16_f32 v5, v5, v7
	v_ashrrev_i32_e32 v7, 31, v6
	v_lshlrev_b64 v[6:7], 12, v[6:7]
	v_lshl_add_u64 v[6:7], s[16:17], 0, v[6:7]
	v_lshl_add_u64 v[6:7], s[10:11], 1, v[6:7]
	v_lshl_add_u64 v[6:7], v[6:7], 0, v[0:1]
	s_cmpk_lt_i32 s13, 0x980
	global_store_dwordx4 v[6:7], v[2:5], off
	s_cbranch_scc0 .LBB0_1437
	s_branch .Lcw1_top

;     ...
;   for (int t = blockIdx.x; t < ntk * ntn; t += gridDim.x) {
;     const int tk = t % ntk, tn = t / ntk, k0 = tk * 64, n0 = tn * 64;
;     __syncthreads();
; #pragma unroll
;     for (int i = 0; i < 2; ++i) {
;       const int id = tid + 512 * i, kr = id >> 4, n4 = (id & 15) * 4;
;       f32x4 v = {0.f, 0.f, 0.f, 0.f};
;       const int nd = n0 + n4, nsrc = (nvalid < 0) ? nd : (nd < csplit ? nd + coff1 : nd + coff2);
;       if (nd < ((nvalid < 0) ? N : nvalid)) v = *(const f32x4*)(W + (size_t)(k0 + kr) * N + nsrc);
;       tile[kr * 65 + n4 + 0] = v[0]; tile[kr * 65 + n4 + 1] = v[1]; tile[kr * 65 + n4 + 2] = v[2]; tile[kr * 65 + n4 + 3] = v[3];
;     }
;     __syncthreads();
;     {
;       const int n = tid >> 3, c = tid & 7;
;       bool rot = false;
;       if (PERM == 1) rot = (n0 == rot_n0);
;       if (PERM == 2) rot = ((tn % 3) == 2);
;       const int ns = rot ? ((n >> 1) + 32 * (n & 1)) : n;
;       if (FP8) {
;         float f[8];
; #pragma unroll
;         for (int j = 0; j < 8; ++j) f[j] = tile[(c * 8 + j) * 65 + ns] * wscale;
;         u32x2 o = {pk4_fp8(f[0], f[1], f[2], f[3]), pk4_fp8(f[4], f[5], f[6], f[7])};
;         *(u32x2*)((unsigned char*)Wt + (size_t)(n0 + n) * K + k0 + c * 8) = o;
;       } else {
;         u32x4 o;
; #pragma unroll
;         for (int j = 0; j < 4; ++j) o[j] = pk2(tile[(c * 8 + 2 * j) * 65 + ns], tile[(c * 8 + 2 * j + 1) * 65 + ns]);
;         *(u32x4*)(Wt + (size_t)(n0 + n) * K + k0 + c * 8) = o;
;       }
;     }
.Lcw2_top:
	s_mov_b32 s100, s13
	s_mov_b32 s101, s12
	s_ashr_i32 s10, s100, 31
	s_lshr_b32 s10, s10, 27
	s_add_i32 s10, s100, s10
	s_ashr_i32 s10, s10, 5
	s_lshl_b32 s15, s10, 6
	s_lshl_b32 s11, s10, 11
	v_or_b32_e32 v17, s15, v10
	s_sub_i32 s16, 0, s11
	v_cmp_gt_i32_e32 vcc, s34, v17
	v_mov_b32_e32 v98, 0
	v_mov_b32_e32 v99, 0
	v_mov_b32_e32 v100, 0
	v_mov_b32_e32 v101, 0
	v_mov_b32_e32 v102, 0
	v_mov_b32_e32 v103, 0
	v_mov_b32_e32 v104, 0
	v_mov_b32_e32 v105, 0
	s_and_saveexec_b64 s[10:11], vcc
	s_movk_i32 s17, 0x800
	v_cmp_gt_i32_e32 vcc, s17, v17
	v_mov_b32_e32 v116, 0x650
	v_readlane_b32 s36, v250, 26
	v_cndmask_b32_e64 v116, v116, 0, vcc
	v_add_u32_e32 v116, v116, v17
	v_ashrrev_i32_e32 v117, 31, v116
	v_readlane_b32 s42, v250, 32
	v_readlane_b32 s43, v250, 33
	s_add_i32 s17, s16, s101
	v_add_u32_e32 v118, s17, v12
	v_lshl_add_u64 v[116:117], v[116:117], 2, s[42:43]
	s_movk_i32 s23, 0x7940
	v_add_u32_e32 v122, s17, v13
	v_mad_i64_i32 v[118:119], s[18:19], v118, s23, v[116:117]
	v_mad_i64_i32 v[116:117], s[18:19], v122, s23, v[116:117]
	global_load_dwordx4 v[98:101], v[118:119], off
	s_nop 0
	global_load_dwordx4 v[102:105], v[116:117], off
	v_readlane_b32 s42, v254, 30
	v_readlane_b32 s37, v250, 27
	v_readlane_b32 s38, v250, 28
	v_readlane_b32 s39, v250, 29
	v_readlane_b32 s40, v250, 30
	v_readlane_b32 s41, v250, 31
	v_readlane_b32 s44, v250, 34
	v_readlane_b32 s45, v250, 35
	v_readlane_b32 s46, v250, 36
	v_readlane_b32 s47, v250, 37
	v_readlane_b32 s48, v250, 38
	v_readlane_b32 s49, v250, 39
	v_readlane_b32 s50, v250, 40
	v_readlane_b32 s51, v250, 41
	v_readlane_b32 s43, v254, 31
	s_or_b64 exec, exec, s[10:11]
	s_add_i32 s100, s100, s33
	s_add_i32 s101, s101, s92
	s_cmpk_lt_i32 s100, 0x600
	s_cselect_b32 s100, s100, s13
	s_cselect_b32 s101, s101, s12
	s_ashr_i32 s10, s100, 31
	s_lshr_b32 s10, s10, 27
	s_add_i32 s10, s100, s10
	s_ashr_i32 s10, s10, 5
	s_lshl_b32 s15, s10, 6
	s_lshl_b32 s11, s10, 11
	v_or_b32_e32 v17, s15, v10
	s_sub_i32 s16, 0, s11
	v_cmp_gt_i32_e32 vcc, s34, v17
	v_mov_b32_e32 v106, 0
	v_mov_b32_e32 v107, 0
	v_mov_b32_e32 v108, 0
	v_mov_b32_e32 v109, 0
	v_mov_b32_e32 v110, 0
	v_mov_b32_e32 v111, 0
	v_mov_b32_e32 v112, 0
	v_mov_b32_e32 v113, 0
	s_and_saveexec_b64 s[10:11], vcc
	s_movk_i32 s17, 0x800
	v_cmp_gt_i32_e32 vcc, s17, v17
	v_mov_b32_e32 v116, 0x650
	v_readlane_b32 s36, v250, 26
	v_cndmask_b32_e64 v116, v116, 0, vcc
	v_add_u32_e32 v116, v116, v17
	v_ashrrev_i32_e32 v117, 31, v116
	v_readlane_b32 s42, v250, 32
	v_readlane_b32 s43, v250, 33
	s_add_i32 s17, s16, s101
	v_add_u32_e32 v118, s17, v12
	v_lshl_add_u64 v[116:117], v[116:117], 2, s[42:43]
	s_movk_i32 s23, 0x7940
	v_add_u32_e32 v122, s17, v13
	v_mad_i64_i32 v[118:119], s[18:19], v118, s23, v[116:117]
	v_mad_i64_i32 v[116:117], s[18:19], v122, s23, v[116:117]
	global_load_dwordx4 v[106:109], v[118:119], off
	s_nop 0
	global_load_dwordx4 v[110:113], v[116:117], off
	v_readlane_b32 s42, v254, 30
	v_readlane_b32 s37, v250, 27
	v_readlane_b32 s38, v250, 28
	v_readlane_b32 s39, v250, 29
	v_readlane_b32 s40, v250, 30
	v_readlane_b32 s41, v250, 31
	v_readlane_b32 s44, v250, 34
	v_readlane_b32 s45, v250, 35
	v_readlane_b32 s46, v250, 36
	v_readlane_b32 s47, v250, 37
	v_readlane_b32 s48, v250, 38
	v_readlane_b32 s49, v250, 39
	v_readlane_b32 s50, v250, 40
	v_readlane_b32 s51, v250, 41
	v_readlane_b32 s43, v254, 31
	s_or_b64 exec, exec, s[10:11]
	s_add_i32 s100, s100, s33
	s_add_i32 s101, s101, s92
	s_cmpk_lt_i32 s100, 0x600
	s_cselect_b32 s100, s100, s13
	s_cselect_b32 s101, s101, s12
	s_ashr_i32 s10, s100, 31
	s_lshr_b32 s10, s10, 27
	s_add_i32 s10, s100, s10
	s_ashr_i32 s10, s10, 5
	s_lshl_b32 s15, s10, 6
	s_lshl_b32 s11, s10, 11
	v_or_b32_e32 v17, s15, v10
	s_sub_i32 s16, 0, s11
	v_cmp_gt_i32_e32 vcc, s34, v17
	v_mov_b32_e32 v208, 0
	v_mov_b32_e32 v209, 0
	v_mov_b32_e32 v210, 0
	v_mov_b32_e32 v211, 0
	v_mov_b32_e32 v212, 0
	v_mov_b32_e32 v213, 0
	v_mov_b32_e32 v214, 0
	v_mov_b32_e32 v215, 0
	s_and_saveexec_b64 s[10:11], vcc
	s_movk_i32 s17, 0x800
	v_cmp_gt_i32_e32 vcc, s17, v17
	v_mov_b32_e32 v116, 0x650
	v_readlane_b32 s36, v250, 26
	v_cndmask_b32_e64 v116, v116, 0, vcc
	v_add_u32_e32 v116, v116, v17
	v_ashrrev_i32_e32 v117, 31, v116
	v_readlane_b32 s42, v250, 32
	v_readlane_b32 s43, v250, 33
	s_add_i32 s17, s16, s101
	v_add_u32_e32 v118, s17, v12
	v_lshl_add_u64 v[116:117], v[116:117], 2, s[42:43]
	s_movk_i32 s23, 0x7940
	v_add_u32_e32 v122, s17, v13
	v_mad_i64_i32 v[118:119], s[18:19], v118, s23, v[116:117]
	v_mad_i64_i32 v[116:117], s[18:19], v122, s23, v[116:117]
	global_load_dwordx4 v[208:211], v[118:119], off
	s_nop 0
	global_load_dwordx4 v[212:215], v[116:117], off
	v_readlane_b32 s42, v254, 30
	v_readlane_b32 s37, v250, 27
	v_readlane_b32 s38, v250, 28
	v_readlane_b32 s39, v250, 29
	v_readlane_b32 s40, v250, 30
	v_readlane_b32 s41, v250, 31
	v_readlane_b32 s44, v250, 34
	v_readlane_b32 s45, v250, 35
	v_readlane_b32 s46, v250, 36
	v_readlane_b32 s47, v250, 37
	v_readlane_b32 s48, v250, 38
	v_readlane_b32 s49, v250, 39
	v_readlane_b32 s50, v250, 40
	v_readlane_b32 s51, v250, 41
	v_readlane_b32 s43, v254, 31
	s_or_b64 exec, exec, s[10:11]
	s_ashr_i32 s10, s13, 31
	s_lshr_b32 s10, s10, 27
	s_add_i32 s10, s13, s10
	s_ashr_i32 s10, s10, 5
	s_lshl_b32 s15, s10, 6
	s_lshl_b32 s11, s10, 11
	v_or_b32_e32 v17, s15, v10
	s_sub_i32 s16, 0, s11
	v_cmp_gt_i32_e32 vcc, s34, v17
	s_waitcnt lgkmcnt(0)
	s_barrier
;     ...
;   for (int t = blockIdx.x; t < ntk * ntn; t += gridDim.x) {
;     const int tk = t % ntk, tn = t / ntk, k0 = tk * 64, n0 = tn * 64;
;     __syncthreads();
; #pragma unroll
;     for (int i = 0; i < 2; ++i) {
;       const int id = tid + 512 * i, kr = id >> 4, n4 = (id & 15) * 4;
;       f32x4 v = {0.f, 0.f, 0.f, 0.f};
;       const int nd = n0 + n4, nsrc = (nvalid < 0) ? nd : (nd < csplit ? nd + coff1 : nd + coff2);
;       if (nd < ((nvalid < 0) ? N : nvalid)) v = *(const f32x4*)(W + (size_t)(k0 + kr) * N + nsrc);
;       tile[kr * 65 + n4 + 0] = v[0]; tile[kr * 65 + n4 + 1] = v[1]; tile[kr * 65 + n4 + 2] = v[2]; tile[kr * 65 + n4 + 3] = v[3];
;     }
;     __syncthreads();
;     {
;       const int n = tid >> 3, c = tid & 7;
;       bool rot = false;
;       if (PERM == 1) rot = (n0 == rot_n0);
;       if (PERM == 2) rot = ((tn % 3) == 2);
;       const int ns = rot ? ((n >> 1) + 32 * (n & 1)) : n;
;       if (FP8) {
;         float f[8];
; #pragma unroll
;         for (int j = 0; j < 8; ++j) f[j] = tile[(c * 8 + j) * 65 + ns] * wscale;
;         u32x2 o = {pk4_fp8(f[0], f[1], f[2], f[3]), pk4_fp8(f[4], f[5], f[6], f[7])};
;         *(u32x2*)((unsigned char*)Wt + (size_t)(n0 + n) * K + k0 + c * 8) = o;
;       } else {
;         u32x4 o;
; #pragma unroll
;         for (int j = 0; j < 4; ++j) o[j] = pk2(tile[(c * 8 + 2 * j) * 65 + ns], tile[(c * 8 + 2 * j + 1) * 65 + ns]);
;         *(u32x4*)(Wt + (size_t)(n0 + n) * K + k0 + c * 8) = o;
;       }
;     }
	s_waitcnt vmcnt(4)
	ds_write2_b32 v14, v98, v99 offset1:1
	ds_write2_b32 v14, v100, v101 offset0:2 offset1:3
	ds_write2_b32 v15, v102, v103 offset1:1
	ds_write2_b32 v15, v104, v105 offset0:2 offset1:3
	s_waitcnt lgkmcnt(0)
	s_barrier
	ds_read2_b32 v[2:3], v16 offset1:65
	ds_read2_b32 v[4:5], v16 offset0:130 offset1:195
	s_add_i32 s10, s12, s16
	s_ashr_i32 s11, s10, 31
	s_add_i32 s13, s13, s33
	s_waitcnt lgkmcnt(1)
	v_mul_f32_e32 v8, 0x43800000, v2
	v_add_u32_e32 v2, 0x400, v16
	ds_read2_b32 v[6:7], v2 offset0:4 offset1:69
	v_mul_f32_e32 v9, 0x43800000, v3
	ds_read2_b32 v[2:3], v2 offset0:134 offset1:199
	s_waitcnt lgkmcnt(2)
	v_mul_f32_e32 v4, 0x43800000, v4
	v_mul_f32_e32 v5, 0x43800000, v5
	s_waitcnt lgkmcnt(1)
	v_mul_f32_e32 v6, 0x43800000, v6
	v_mul_f32_e32 v7, 0x43800000, v7
	s_waitcnt lgkmcnt(0)
	v_mul_f32_e32 v17, 0x43800000, v2
	v_mul_f32_e32 v18, 0x43800000, v3
	v_med3_f32 v3, v8, s93, v223
	v_med3_f32 v8, v9, s93, v223
	v_mov_b32_e32 v2, v1
	v_cvt_pk_fp8_f32 v2, v3, v8
	v_med3_f32 v6, v6, s93, v223
	v_med3_f32 v7, v7, s93, v223
	v_mov_b32_e32 v3, v1
	v_cvt_pk_fp8_f32 v3, v6, v7
	v_med3_f32 v4, v4, s93, v223
	v_med3_f32 v5, v5, s93, v223
	v_cvt_pk_fp8_f32 v2, v4, v5 op_sel:[0,0,1]
	v_med3_f32 v4, v17, s93, v223
	v_med3_f32 v5, v18, s93, v223
	v_cvt_pk_fp8_f32 v3, v4, v5 op_sel:[0,0,1]
	v_add_u32_e32 v4, s15, v11
	v_ashrrev_i32_e32 v5, 31, v4
	v_lshlrev_b64 v[4:5], 11, v[4:5]
	v_lshl_add_u64 v[4:5], s[6:7], 0, v[4:5]
	v_lshl_add_u64 v[4:5], v[4:5], 0, s[10:11]
	s_add_i32 s12, s12, s92
	v_lshl_add_u64 v[4:5], v[4:5], 0, v[0:1]
	s_cmpk_gt_i32 s13, 0x5ff
	global_store_dwordx2 v[4:5], v[2:3], off
	s_cbranch_scc1 .Lcw2_x1
	s_ashr_i32 s10, s13, 31
	s_lshr_b32 s10, s10, 27
	s_add_i32 s10, s13, s10
	s_ashr_i32 s10, s10, 5
	s_lshl_b32 s15, s10, 6
	s_lshl_b32 s11, s10, 11
	v_or_b32_e32 v17, s15, v10
	s_sub_i32 s16, 0, s11
	v_cmp_gt_i32_e32 vcc, s34, v17
	s_waitcnt lgkmcnt(0)
	s_barrier
	s_waitcnt vmcnt(3)
	ds_write2_b32 v14, v106, v107 offset1:1
	ds_write2_b32 v14, v108, v109 offset0:2 offset1:3
	ds_write2_b32 v15, v110, v111 offset1:1
	ds_write2_b32 v15, v112, v113 offset0:2 offset1:3
	s_waitcnt lgkmcnt(0)
	s_barrier
	ds_read2_b32 v[2:3], v16 offset1:65
	ds_read2_b32 v[4:5], v16 offset0:130 offset1:195
	s_add_i32 s10, s12, s16
	s_ashr_i32 s11, s10, 31
	s_add_i32 s13, s13, s33
	s_waitcnt lgkmcnt(1)
	v_mul_f32_e32 v8, 0x43800000, v2
	v_add_u32_e32 v2, 0x400, v16
	ds_read2_b32 v[6:7], v2 offset0:4 offset1:69
	v_mul_f32_e32 v9, 0x43800000, v3
	ds_read2_b32 v[2:3], v2 offset0:134 offset1:199
	s_waitcnt lgkmcnt(2)
	v_mul_f32_e32 v4, 0x43800000, v4
	v_mul_f32_e32 v5, 0x43800000, v5
	s_waitcnt lgkmcnt(1)
	v_mul_f32_e32 v6, 0x43800000, v6
	v_mul_f32_e32 v7, 0x43800000, v7
	s_waitcnt lgkmcnt(0)
	v_mul_f32_e32 v17, 0x43800000, v2
	v_mul_f32_e32 v18, 0x43800000, v3
	v_med3_f32 v3, v8, s93, v223
	v_med3_f32 v8, v9, s93, v223
	v_mov_b32_e32 v2, v1
	v_cvt_pk_fp8_f32 v2, v3, v8
	v_med3_f32 v6, v6, s93, v223
	v_med3_f32 v7, v7, s93, v223
	v_mov_b32_e32 v3, v1
	v_cvt_pk_fp8_f32 v3, v6, v7
	v_med3_f32 v4, v4, s93, v223
	v_med3_f32 v5, v5, s93, v223
	v_cvt_pk_fp8_f32 v2, v4, v5 op_sel:[0,0,1]
	v_med3_f32 v4, v17, s93, v223
	v_med3_f32 v5, v18, s93, v223
	v_cvt_pk_fp8_f32 v3, v4, v5 op_sel:[0,0,1]
	v_add_u32_e32 v4, s15, v11
	v_ashrrev_i32_e32 v5, 31, v4
	v_lshlrev_b64 v[4:5], 11, v[4:5]
	v_lshl_add_u64 v[4:5], s[6:7], 0, v[4:5]
	v_lshl_add_u64 v[4:5], v[4:5], 0, s[10:11]
	s_add_i32 s12, s12, s92
	v_lshl_add_u64 v[4:5], v[4:5], 0, v[0:1]
	s_cmpk_gt_i32 s13, 0x5ff
	global_store_dwordx2 v[4:5], v[2:3], off
	s_cbranch_scc1 .Lcw2_x2
	s_ashr_i32 s10, s13, 31
	s_lshr_b32 s10, s10, 27
	s_add_i32 s10, s13, s10
	s_ashr_i32 s10, s10, 5
	s_lshl_b32 s15, s10, 6
	s_lshl_b32 s11, s10, 11
	v_or_b32_e32 v17, s15, v10
	s_sub_i32 s16, 0, s11
	v_cmp_gt_i32_e32 vcc, s34, v17
	s_waitcnt lgkmcnt(0)
	s_barrier
	s_waitcnt vmcnt(2)
	ds_write2_b32 v14, v208, v209 offset1:1
	ds_write2_b32 v14, v210, v211 offset0:2 offset1:3
	ds_write2_b32 v15, v212, v213 offset1:1
	ds_write2_b32 v15, v214, v215 offset0:2 offset1:3
	s_waitcnt lgkmcnt(0)
	s_barrier
	ds_read2_b32 v[2:3], v16 offset1:65
	ds_read2_b32 v[4:5], v16 offset0:130 offset1:195
	s_add_i32 s10, s12, s16
	s_ashr_i32 s11, s10, 31
	s_add_i32 s13, s13, s33
	s_waitcnt lgkmcnt(1)
	v_mul_f32_e32 v8, 0x43800000, v2
	v_add_u32_e32 v2, 0x400, v16
	ds_read2_b32 v[6:7], v2 offset0:4 offset1:69
	v_mul_f32_e32 v9, 0x43800000, v3
	ds_read2_b32 v[2:3], v2 offset0:134 offset1:199
	s_waitcnt lgkmcnt(2)
	v_mul_f32_e32 v4, 0x43800000, v4
	v_mul_f32_e32 v5, 0x43800000, v5
	s_waitcnt lgkmcnt(1)
	v_mul_f32_e32 v6, 0x43800000, v6
	v_mul_f32_e32 v7, 0x43800000, v7
	s_waitcnt lgkmcnt(0)
	v_mul_f32_e32 v17, 0x43800000, v2
	v_mul_f32_e32 v18, 0x43800000, v3
	v_med3_f32 v3, v8, s93, v223
	v_med3_f32 v8, v9, s93, v223
	v_mov_b32_e32 v2, v1
	v_cvt_pk_fp8_f32 v2, v3, v8
	v_med3_f32 v6, v6, s93, v223
	v_med3_f32 v7, v7, s93, v223
	v_mov_b32_e32 v3, v1
	v_cvt_pk_fp8_f32 v3, v6, v7
	v_med3_f32 v4, v4, s93, v223
	v_med3_f32 v5, v5, s93, v223
	v_cvt_pk_fp8_f32 v2, v4, v5 op_sel:[0,0,1]
	v_med3_f32 v4, v17, s93, v223
	v_med3_f32 v5, v18, s93, v223
	v_cvt_pk_fp8_f32 v3, v4, v5 op_sel:[0,0,1]
	v_add_u32_e32 v4, s15, v11
	v_ashrrev_i32_e32 v5, 31, v4
	v_lshlrev_b64 v[4:5], 11, v[4:5]
	v_lshl_add_u64 v[4:5], s[6:7], 0, v[4:5]
	v_lshl_add_u64 v[4:5], v[4:5], 0, s[10:11]
	s_add_i32 s12, s12, s92
	v_lshl_add_u64 v[4:5], v[4:5], 0, v[0:1]
	s_cmpk_gt_i32 s13, 0x5ff
	global_store_dwordx2 v[4:5], v[2:3], off
	s_cbranch_scc1 .LBB0_1442
	s_branch .Lcw2_top

;     ...
;   for (int t = blockIdx.x; t < ntk * ntn; t += gridDim.x) {
;     const int tk = t % ntk, tn = t / ntk, k0 = tk * 64, n0 = tn * 64;
;     __syncthreads();
; #pragma unroll
;     for (int i = 0; i < 2; ++i) {
;       const int id = tid + 512 * i, kr = id >> 4, n4 = (id & 15) * 4;
;       f32x4 v = {0.f, 0.f, 0.f, 0.f};
;       const int nd = n0 + n4, nsrc = (nvalid < 0) ? nd : (nd < csplit ? nd + coff1 : nd + coff2);
;       if (nd < ((nvalid < 0) ? N : nvalid)) v = *(const f32x4*)(W + (size_t)(k0 + kr) * N + nsrc);
;       tile[kr * 65 + n4 + 0] = v[0]; tile[kr * 65 + n4 + 1] = v[1]; tile[kr * 65 + n4 + 2] = v[2]; tile[kr * 65 + n4 + 3] = v[3];
;     }
;     __syncthreads();
;     {
;       const int n = tid >> 3, c = tid & 7;
;       bool rot = false;
;       if (PERM == 1) rot = (n0 == rot_n0);
;       if (PERM == 2) rot = ((tn % 3) == 2);
;       const int ns = rot ? ((n >> 1) + 32 * (n & 1)) : n;
;       if (FP8) {
;         float f[8];
; #pragma unroll
;         for (int j = 0; j < 8; ++j) f[j] = tile[(c * 8 + j) * 65 + ns] * wscale;
;         u32x2 o = {pk4_fp8(f[0], f[1], f[2], f[3]), pk4_fp8(f[4], f[5], f[6], f[7])};
;         *(u32x2*)((unsigned char*)Wt + (size_t)(n0 + n) * K + k0 + c * 8) = o;
;       } else {
;         u32x4 o;
; #pragma unroll
;         for (int j = 0; j < 4; ++j) o[j] = pk2(tile[(c * 8 + 2 * j) * 65 + ns], tile[(c * 8 + 2 * j + 1) * 65 + ns]);
;         *(u32x4*)(Wt + (size_t)(n0 + n) * K + k0 + c * 8) = o;
;       }
;     }
.Lcw3_top:
	s_mov_b32 s100, s11
	s_mov_b32 s101, s10
	s_ashr_i32 s0, s100, 31
	s_lshr_b32 s0, s0, 27
	s_add_i32 s0, s100, s0
	s_ashr_i32 s0, s0, 5
	s_lshl_b32 s12, s0, 6
	s_lshl_b32 s1, s0, 11
	v_or_b32_e32 v18, s12, v10
	s_movk_i32 s0, 0xe00
	s_sub_i32 s13, 0, s1
	v_cmp_gt_i32_e32 vcc, s0, v18
	v_mov_b32_e32 v98, 0
	v_mov_b32_e32 v99, 0
	v_mov_b32_e32 v100, 0
	v_mov_b32_e32 v101, 0
	v_mov_b32_e32 v102, 0
	v_mov_b32_e32 v103, 0
	v_mov_b32_e32 v104, 0
	v_mov_b32_e32 v105, 0
	s_and_saveexec_b64 s[0:1], vcc
	s_movk_i32 s14, 0x200
	v_cmp_gt_i32_e32 vcc, s14, v18
	v_mov_b32_e32 v116, 0xc00
	v_readlane_b32 s36, v250, 26
	v_cndmask_b32_e32 v116, v116, v235, vcc
	s_add_i32 s16, s13, s101
	v_readlane_b32 s44, v250, 34
	v_readlane_b32 s45, v250, 35
	v_add_u32_e32 v116, v116, v18
	v_add_u32_e32 v117, s16, v13
	v_mov_b64_e32 v[118:119], s[44:45]
	v_mad_i64_i32 v[122:123], s[14:15], v117, s22, v[118:119]
	v_ashrrev_i32_e32 v117, 31, v116
	v_add_u32_e32 v124, s16, v14
	v_lshlrev_b64 v[116:117], 2, v[116:117]
	v_mad_i64_i32 v[118:119], s[14:15], v124, s22, v[118:119]
	v_lshl_add_u64 v[122:123], v[122:123], 0, v[116:117]
	v_lshl_add_u64 v[116:117], v[118:119], 0, v[116:117]
	global_load_dwordx4 v[98:101], v[122:123], off
	s_nop 0
	global_load_dwordx4 v[102:105], v[116:117], off
	v_readlane_b32 s42, v250, 32
	v_readlane_b32 s43, v250, 33
	v_readlane_b32 s42, v254, 30
	v_readlane_b32 s37, v250, 27
	v_readlane_b32 s38, v250, 28
	v_readlane_b32 s39, v250, 29
	v_readlane_b32 s40, v250, 30
	v_readlane_b32 s41, v250, 31
	v_readlane_b32 s46, v250, 36
	v_readlane_b32 s47, v250, 37
	v_readlane_b32 s48, v250, 38
	v_readlane_b32 s49, v250, 39
	v_readlane_b32 s50, v250, 40
	v_readlane_b32 s51, v250, 41
	v_readlane_b32 s43, v254, 31
	s_or_b64 exec, exec, s[0:1]
	s_add_i32 s100, s100, s33
	s_add_i32 s101, s101, s92
	s_cmpk_lt_i32 s100, 0x700
	s_cselect_b32 s100, s100, s11
	s_cselect_b32 s101, s101, s10
	s_ashr_i32 s0, s100, 31
	s_lshr_b32 s0, s0, 27
	s_add_i32 s0, s100, s0
	s_ashr_i32 s0, s0, 5
	s_lshl_b32 s12, s0, 6
	s_lshl_b32 s1, s0, 11
	v_or_b32_e32 v18, s12, v10
	s_movk_i32 s0, 0xe00
	s_sub_i32 s13, 0, s1
	v_cmp_gt_i32_e32 vcc, s0, v18
	v_mov_b32_e32 v106, 0
	v_mov_b32_e32 v107, 0
	v_mov_b32_e32 v108, 0
	v_mov_b32_e32 v109, 0
	v_mov_b32_e32 v110, 0
	v_mov_b32_e32 v111, 0
	v_mov_b32_e32 v112, 0
	v_mov_b32_e32 v113, 0
	s_and_saveexec_b64 s[0:1], vcc
	s_movk_i32 s14, 0x200
	v_cmp_gt_i32_e32 vcc, s14, v18
	v_mov_b32_e32 v116, 0xc00
	v_readlane_b32 s36, v250, 26
	v_cndmask_b32_e32 v116, v116, v235, vcc
	s_add_i32 s16, s13, s101
	v_readlane_b32 s44, v250, 34
	v_readlane_b32 s45, v250, 35
	v_add_u32_e32 v116, v116, v18
	v_add_u32_e32 v117, s16, v13
	v_mov_b64_e32 v[118:119], s[44:45]
	v_mad_i64_i32 v[122:123], s[14:15], v117, s22, v[118:119]
	v_ashrrev_i32_e32 v117, 31, v116
	v_add_u32_e32 v124, s16, v14
	v_lshlrev_b64 v[116:117], 2, v[116:117]
	v_mad_i64_i32 v[118:119], s[14:15], v124, s22, v[118:119]
	v_lshl_add_u64 v[122:123], v[122:123], 0, v[116:117]
	v_lshl_add_u64 v[116:117], v[118:119], 0, v[116:117]
	global_load_dwordx4 v[106:109], v[122:123], off
	s_nop 0
	global_load_dwordx4 v[110:113], v[116:117], off
	v_readlane_b32 s42, v250, 32
	v_readlane_b32 s43, v250, 33
	v_readlane_b32 s42, v254, 30
	v_readlane_b32 s37, v250, 27
	v_readlane_b32 s38, v250, 28
	v_readlane_b32 s39, v250, 29
	v_readlane_b32 s40, v250, 30
	v_readlane_b32 s41, v250, 31
	v_readlane_b32 s46, v250, 36
	v_readlane_b32 s47, v250, 37
	v_readlane_b32 s48, v250, 38
	v_readlane_b32 s49, v250, 39
	v_readlane_b32 s50, v250, 40
	v_readlane_b32 s51, v250, 41
	v_readlane_b32 s43, v254, 31
	s_or_b64 exec, exec, s[0:1]
	s_add_i32 s100, s100, s33
	s_add_i32 s101, s101, s92
	s_cmpk_lt_i32 s100, 0x700
	s_cselect_b32 s100, s100, s11
	s_cselect_b32 s101, s101, s10
	s_ashr_i32 s0, s100, 31
	s_lshr_b32 s0, s0, 27
	s_add_i32 s0, s100, s0
	s_ashr_i32 s0, s0, 5
	s_lshl_b32 s12, s0, 6
	s_lshl_b32 s1, s0, 11
	v_or_b32_e32 v18, s12, v10
	s_movk_i32 s0, 0xe00
	s_sub_i32 s13, 0, s1
	v_cmp_gt_i32_e32 vcc, s0, v18
	v_mov_b32_e32 v208, 0
	v_mov_b32_e32 v209, 0
	v_mov_b32_e32 v210, 0
	v_mov_b32_e32 v211, 0
	v_mov_b32_e32 v212, 0
	v_mov_b32_e32 v213, 0
	v_mov_b32_e32 v214, 0
	v_mov_b32_e32 v215, 0
	s_and_saveexec_b64 s[0:1], vcc
	s_movk_i32 s14, 0x200
	v_cmp_gt_i32_e32 vcc, s14, v18
	v_mov_b32_e32 v116, 0xc00
	v_readlane_b32 s36, v250, 26
	v_cndmask_b32_e32 v116, v116, v235, vcc
	s_add_i32 s16, s13, s101
	v_readlane_b32 s44, v250, 34
	v_readlane_b32 s45, v250, 35
	v_add_u32_e32 v116, v116, v18
	v_add_u32_e32 v117, s16, v13
	v_mov_b64_e32 v[118:119], s[44:45]
	v_mad_i64_i32 v[122:123], s[14:15], v117, s22, v[118:119]
	v_ashrrev_i32_e32 v117, 31, v116
	v_add_u32_e32 v124, s16, v14
	v_lshlrev_b64 v[116:117], 2, v[116:117]
	v_mad_i64_i32 v[118:119], s[14:15], v124, s22, v[118:119]
	v_lshl_add_u64 v[122:123], v[122:123], 0, v[116:117]
	v_lshl_add_u64 v[116:117], v[118:119], 0, v[116:117]
	global_load_dwordx4 v[208:211], v[122:123], off
	s_nop 0
	global_load_dwordx4 v[212:215], v[116:117], off
	v_readlane_b32 s42, v250, 32
	v_readlane_b32 s43, v250, 33
	v_readlane_b32 s42, v254, 30
	v_readlane_b32 s37, v250, 27
	v_readlane_b32 s38, v250, 28
	v_readlane_b32 s39, v250, 29
	v_readlane_b32 s40, v250, 30
	v_readlane_b32 s41, v250, 31
	v_readlane_b32 s46, v250, 36
	v_readlane_b32 s47, v250, 37
	v_readlane_b32 s48, v250, 38
	v_readlane_b32 s49, v250, 39
	v_readlane_b32 s50, v250, 40
	v_readlane_b32 s51, v250, 41
	v_readlane_b32 s43, v254, 31
	s_or_b64 exec, exec, s[0:1]
	s_ashr_i32 s0, s11, 31
	s_lshr_b32 s0, s0, 27
	s_add_i32 s0, s11, s0
	s_ashr_i32 s0, s0, 5
	s_lshl_b32 s12, s0, 6
	s_lshl_b32 s1, s0, 11
	v_or_b32_e32 v18, s12, v10
	s_movk_i32 s0, 0xe00
	s_sub_i32 s13, 0, s1
	v_cmp_gt_i32_e32 vcc, s0, v18
	s_waitcnt lgkmcnt(0)
	s_barrier
;     ...
;   for (int t = blockIdx.x; t < ntk * ntn; t += gridDim.x) {
;     const int tk = t % ntk, tn = t / ntk, k0 = tk * 64, n0 = tn * 64;
;     __syncthreads();
; #pragma unroll
;     for (int i = 0; i < 2; ++i) {
;       const int id = tid + 512 * i, kr = id >> 4, n4 = (id & 15) * 4;
;       f32x4 v = {0.f, 0.f, 0.f, 0.f};
;       const int nd = n0 + n4, nsrc = (nvalid < 0) ? nd : (nd < csplit ? nd + coff1 : nd + coff2);
;       if (nd < ((nvalid < 0) ? N : nvalid)) v = *(const f32x4*)(W + (size_t)(k0 + kr) * N + nsrc);
;       tile[kr * 65 + n4 + 0] = v[0]; tile[kr * 65 + n4 + 1] = v[1]; tile[kr * 65 + n4 + 2] = v[2]; tile[kr * 65 + n4 + 3] = v[3];
;     }
;     __syncthreads();
;     {
;       const int n = tid >> 3, c = tid & 7;
;       bool rot = false;
;       if (PERM == 1) rot = (n0 == rot_n0);
;       if (PERM == 2) rot = ((tn % 3) == 2);
;       const int ns = rot ? ((n >> 1) + 32 * (n & 1)) : n;
;       if (FP8) {
;         float f[8];
; #pragma unroll
;         for (int j = 0; j < 8; ++j) f[j] = tile[(c * 8 + j) * 65 + ns] * wscale;
;         u32x2 o = {pk4_fp8(f[0], f[1], f[2], f[3]), pk4_fp8(f[4], f[5], f[6], f[7])};
;         *(u32x2*)((unsigned char*)Wt + (size_t)(n0 + n) * K + k0 + c * 8) = o;
;       } else {
;         u32x4 o;
; #pragma unroll
;         for (int j = 0; j < 4; ++j) o[j] = pk2(tile[(c * 8 + 2 * j) * 65 + ns], tile[(c * 8 + 2 * j + 1) * 65 + ns]);
;         *(u32x4*)(Wt + (size_t)(n0 + n) * K + k0 + c * 8) = o;
;       }
;     }
	s_waitcnt vmcnt(4)
	ds_write2_b32 v16, v98, v99 offset1:1
	ds_write2_b32 v16, v100, v101 offset0:2 offset1:3
	ds_write2_b32 v17, v102, v103 offset1:1
	ds_write2_b32 v17, v104, v105 offset0:2 offset1:3
	s_waitcnt lgkmcnt(0)
	s_barrier
	ds_read2_b32 v[2:3], v12 offset1:130
	ds_read2_b32 v[4:5], v15 offset0:65 offset1:195
	v_add_u32_e32 v6, 0x400, v15
	ds_read2_b32 v[6:7], v6 offset0:69 offset1:199
	s_add_i32 s0, s10, s13
	s_ashr_i32 s1, s0, 31
	s_waitcnt lgkmcnt(1)
	v_cvt_pk_bf16_f32 v2, v2, v4
	v_add_u32_e32 v4, 0x400, v12
	v_cvt_pk_bf16_f32 v3, v3, v5
	ds_read2_b32 v[4:5], v4 offset0:4 offset1:134
	s_add_i32 s11, s11, s33
	s_add_i32 s10, s10, s92
	s_cmpk_lt_i32 s11, 0x700
	s_waitcnt lgkmcnt(0)
	v_cvt_pk_bf16_f32 v4, v4, v6
	v_add_u32_e32 v6, s12, v11
	v_cvt_pk_bf16_f32 v5, v5, v7
	v_ashrrev_i32_e32 v7, 31, v6
	v_readlane_b32 s12, v253, 15
	v_lshlrev_b64 v[6:7], 12, v[6:7]
	v_readlane_b32 s13, v253, 16
	s_nop 1
	v_lshl_add_u64 v[6:7], s[12:13], 0, v[6:7]
	v_lshl_add_u64 v[6:7], s[0:1], 1, v[6:7]
	v_lshl_add_u64 v[6:7], v[6:7], 0, v[0:1]
	global_store_dwordx4 v[6:7], v[2:5], off
	s_cbranch_scc0 .Lcw3_x1
	s_ashr_i32 s0, s11, 31
	s_lshr_b32 s0, s0, 27
	s_add_i32 s0, s11, s0
	s_ashr_i32 s0, s0, 5
	s_lshl_b32 s12, s0, 6
	s_lshl_b32 s1, s0, 11
	v_or_b32_e32 v18, s12, v10
	s_movk_i32 s0, 0xe00
	s_sub_i32 s13, 0, s1
	v_cmp_gt_i32_e32 vcc, s0, v18
	s_waitcnt lgkmcnt(0)
	s_barrier
	s_waitcnt vmcnt(3)
	ds_write2_b32 v16, v106, v107 offset1:1
	ds_write2_b32 v16, v108, v109 offset0:2 offset1:3
	ds_write2_b32 v17, v110, v111 offset1:1
	ds_write2_b32 v17, v112, v113 offset0:2 offset1:3
	s_waitcnt lgkmcnt(0)
	s_barrier
	ds_read2_b32 v[2:3], v12 offset1:130
	ds_read2_b32 v[4:5], v15 offset0:65 offset1:195
	v_add_u32_e32 v6, 0x400, v15
	ds_read2_b32 v[6:7], v6 offset0:69 offset1:199
	s_add_i32 s0, s10, s13
	s_ashr_i32 s1, s0, 31
	s_waitcnt lgkmcnt(1)
	v_cvt_pk_bf16_f32 v2, v2, v4
	v_add_u32_e32 v4, 0x400, v12
	v_cvt_pk_bf16_f32 v3, v3, v5
	ds_read2_b32 v[4:5], v4 offset0:4 offset1:134
	s_add_i32 s11, s11, s33
	s_add_i32 s10, s10, s92
	s_cmpk_lt_i32 s11, 0x700
	s_waitcnt lgkmcnt(0)
	v_cvt_pk_bf16_f32 v4, v4, v6
	v_add_u32_e32 v6, s12, v11
	v_cvt_pk_bf16_f32 v5, v5, v7
	v_ashrrev_i32_e32 v7, 31, v6
	v_readlane_b32 s12, v253, 15
	v_lshlrev_b64 v[6:7], 12, v[6:7]
	v_readlane_b32 s13, v253, 16
	s_nop 1
	v_lshl_add_u64 v[6:7], s[12:13], 0, v[6:7]
	v_lshl_add_u64 v[6:7], s[0:1], 1, v[6:7]
	v_lshl_add_u64 v[6:7], v[6:7], 0, v[0:1]
	global_store_dwordx4 v[6:7], v[2:5], off
	s_cbranch_scc0 .Lcw3_x2
	s_ashr_i32 s0, s11, 31
	s_lshr_b32 s0, s0, 27
	s_add_i32 s0, s11, s0
	s_ashr_i32 s0, s0, 5
	s_lshl_b32 s12, s0, 6
	s_lshl_b32 s1, s0, 11
	v_or_b32_e32 v18, s12, v10
	s_movk_i32 s0, 0xe00
	s_sub_i32 s13, 0, s1
	v_cmp_gt_i32_e32 vcc, s0, v18
	s_waitcnt lgkmcnt(0)
	s_barrier
	s_waitcnt vmcnt(2)
	ds_write2_b32 v16, v208, v209 offset1:1
	ds_write2_b32 v16, v210, v211 offset0:2 offset1:3
	ds_write2_b32 v17, v212, v213 offset1:1
	ds_write2_b32 v17, v214, v215 offset0:2 offset1:3
	s_waitcnt lgkmcnt(0)
	s_barrier
	ds_read2_b32 v[2:3], v12 offset1:130
	ds_read2_b32 v[4:5], v15 offset0:65 offset1:195
	v_add_u32_e32 v6, 0x400, v15
	ds_read2_b32 v[6:7], v6 offset0:69 offset1:199
	s_add_i32 s0, s10, s13
	s_ashr_i32 s1, s0, 31
	s_waitcnt lgkmcnt(1)
	v_cvt_pk_bf16_f32 v2, v2, v4
	v_add_u32_e32 v4, 0x400, v12
	v_cvt_pk_bf16_f32 v3, v3, v5
	ds_read2_b32 v[4:5], v4 offset0:4 offset1:134
	s_add_i32 s11, s11, s33
	s_add_i32 s10, s10, s92
	s_cmpk_lt_i32 s11, 0x700
	s_waitcnt lgkmcnt(0)
	v_cvt_pk_bf16_f32 v4, v4, v6
	v_add_u32_e32 v6, s12, v11
	v_cvt_pk_bf16_f32 v5, v5, v7
	v_ashrrev_i32_e32 v7, 31, v6
	v_readlane_b32 s12, v253, 15
	v_lshlrev_b64 v[6:7], 12, v[6:7]
	v_readlane_b32 s13, v253, 16
	s_nop 1
	v_lshl_add_u64 v[6:7], s[12:13], 0, v[6:7]
	v_lshl_add_u64 v[6:7], s[0:1], 1, v[6:7]
	v_lshl_add_u64 v[6:7], v[6:7], 0, v[0:1]
	global_store_dwordx4 v[6:7], v[2:5], off
	s_cbranch_scc0 .LBB0_1450
	s_branch .Lcw3_top

;     ...
;   for (int t = blockIdx.x; t < ntk * ntn; t += gridDim.x) {
;     const int tk = t % ntk, tn = t / ntk, k0 = tk * 64, n0 = tn * 64;
;     __syncthreads();
; #pragma unroll
;     for (int i = 0; i < 2; ++i) {
;       const int id = tid + 512 * i, kr = id >> 4, n4 = (id & 15) * 4;
;       f32x4 v = {0.f, 0.f, 0.f, 0.f};
;       const int nd = n0 + n4, nsrc = (nvalid < 0) ? nd : (nd < csplit ? nd + coff1 : nd + coff2);
;       if (nd < ((nvalid < 0) ? N : nvalid)) v = *(const f32x4*)(W + (size_t)(k0 + kr) * N + nsrc);
;       tile[kr * 65 + n4 + 0] = v[0]; tile[kr * 65 + n4 + 1] = v[1]; tile[kr * 65 + n4 + 2] = v[2]; tile[kr * 65 + n4 + 3] = v[3];
;     }
;     __syncthreads();
;     {
;       const int n = tid >> 3, c = tid & 7;
;       bool rot = false;
;       if (PERM == 1) rot = (n0 == rot_n0);
;       if (PERM == 2) rot = ((tn % 3) == 2);
;       const int ns = rot ? ((n >> 1) + 32 * (n & 1)) : n;
;       if (FP8) {
;         float f[8];
; #pragma unroll
;         for (int j = 0; j < 8; ++j) f[j] = tile[(c * 8 + j) * 65 + ns] * wscale;
;         u32x2 o = {pk4_fp8(f[0], f[1], f[2], f[3]), pk4_fp8(f[4], f[5], f[6], f[7])};
;         *(u32x2*)((unsigned char*)Wt + (size_t)(n0 + n) * K + k0 + c * 8) = o;
;       } else {
;         u32x4 o;
; #pragma unroll
;         for (int j = 0; j < 4; ++j) o[j] = pk2(tile[(c * 8 + 2 * j) * 65 + ns], tile[(c * 8 + 2 * j + 1) * 65 + ns]);
;         *(u32x4*)(Wt + (size_t)(n0 + n) * K + k0 + c * 8) = o;
;       }
;     }
.Lcw4_top:
	s_mov_b32 s100, s9
	s_mov_b32 s101, s8
	s_ashr_i32 s0, s100, 31
	s_lshr_b32 s0, s0, 27
	s_add_i32 s0, s100, s0
	s_ashr_i32 s0, s0, 5
	s_lshl_b32 s10, s0, 6
	s_lshl_b32 s1, s0, 11
	v_or_b32_e32 v17, s10, v10
	s_sub_i32 s11, 0, s1
	v_cmp_gt_i32_e32 vcc, s34, v17
	v_mov_b32_e32 v98, 0
	v_mov_b32_e32 v99, 0
	v_mov_b32_e32 v100, 0
	v_mov_b32_e32 v101, 0
	v_mov_b32_e32 v102, 0
	v_mov_b32_e32 v103, 0
	v_mov_b32_e32 v104, 0
	v_mov_b32_e32 v105, 0
	s_and_saveexec_b64 s[0:1], vcc
	s_movk_i32 s12, 0x800
	v_cmp_gt_i32_e32 vcc, s12, v17
	v_mov_b32_e32 v116, 0x200
	v_readlane_b32 s36, v250, 26
	v_cndmask_b32_e64 v116, v116, 0, vcc
	v_add_u32_e32 v116, v116, v17
	v_ashrrev_i32_e32 v117, 31, v116
	v_readlane_b32 s44, v250, 34
	v_readlane_b32 s45, v250, 35
	s_add_i32 s14, s11, s101
	v_add_u32_e32 v118, s14, v12
	v_lshl_add_u64 v[116:117], v[116:117], 2, s[44:45]
	v_add_u32_e32 v122, s14, v13
	v_mad_i64_i32 v[118:119], s[12:13], v118, s22, v[116:117]
	v_mad_i64_i32 v[116:117], s[12:13], v122, s22, v[116:117]
	global_load_dwordx4 v[98:101], v[118:119], off
	s_nop 0
	global_load_dwordx4 v[102:105], v[116:117], off
	v_readlane_b32 s42, v250, 32
	v_readlane_b32 s43, v250, 33
	v_readlane_b32 s42, v254, 30
	v_readlane_b32 s37, v250, 27
	v_readlane_b32 s38, v250, 28
	v_readlane_b32 s39, v250, 29
	v_readlane_b32 s40, v250, 30
	v_readlane_b32 s41, v250, 31
	v_readlane_b32 s46, v250, 36
	v_readlane_b32 s47, v250, 37
	v_readlane_b32 s48, v250, 38
	v_readlane_b32 s49, v250, 39
	v_readlane_b32 s50, v250, 40
	v_readlane_b32 s51, v250, 41
	v_readlane_b32 s43, v254, 31
	s_or_b64 exec, exec, s[0:1]
	s_add_i32 s100, s100, s33
	s_add_i32 s101, s101, s92
	s_cmpk_lt_i32 s100, 0x600
	s_cselect_b32 s100, s100, s9
	s_cselect_b32 s101, s101, s8
	s_ashr_i32 s0, s100, 31
	s_lshr_b32 s0, s0, 27
	s_add_i32 s0, s100, s0
	s_ashr_i32 s0, s0, 5
	s_lshl_b32 s10, s0, 6
	s_lshl_b32 s1, s0, 11
	v_or_b32_e32 v17, s10, v10
	s_sub_i32 s11, 0, s1
	v_cmp_gt_i32_e32 vcc, s34, v17
	v_mov_b32_e32 v106, 0
	v_mov_b32_e32 v107, 0
	v_mov_b32_e32 v108, 0
	v_mov_b32_e32 v109, 0
	v_mov_b32_e32 v110, 0
	v_mov_b32_e32 v111, 0
	v_mov_b32_e32 v112, 0
	v_mov_b32_e32 v113, 0
	s_and_saveexec_b64 s[0:1], vcc
	s_movk_i32 s12, 0x800
	v_cmp_gt_i32_e32 vcc, s12, v17
	v_mov_b32_e32 v116, 0x200
	v_readlane_b32 s36, v250, 26
	v_cndmask_b32_e64 v116, v116, 0, vcc
	v_add_u32_e32 v116, v116, v17
	v_ashrrev_i32_e32 v117, 31, v116
	v_readlane_b32 s44, v250, 34
	v_readlane_b32 s45, v250, 35
	s_add_i32 s14, s11, s101
	v_add_u32_e32 v118, s14, v12
	v_lshl_add_u64 v[116:117], v[116:117], 2, s[44:45]
	v_add_u32_e32 v122, s14, v13
	v_mad_i64_i32 v[118:119], s[12:13], v118, s22, v[116:117]
	v_mad_i64_i32 v[116:117], s[12:13], v122, s22, v[116:117]
	global_load_dwordx4 v[106:109], v[118:119], off
	s_nop 0
	global_load_dwordx4 v[110:113], v[116:117], off
	v_readlane_b32 s42, v250, 32
	v_readlane_b32 s43, v250, 33
	v_readlane_b32 s42, v254, 30
	v_readlane_b32 s37, v250, 27
	v_readlane_b32 s38, v250, 28
	v_readlane_b32 s39, v250, 29
	v_readlane_b32 s40, v250, 30
	v_readlane_b32 s41, v250, 31
	v_readlane_b32 s46, v250, 36
	v_readlane_b32 s47, v250, 37
	v_readlane_b32 s48, v250, 38
	v_readlane_b32 s49, v250, 39
	v_readlane_b32 s50, v250, 40
	v_readlane_b32 s51, v250, 41
	v_readlane_b32 s43, v254, 31
	s_or_b64 exec, exec, s[0:1]
	s_add_i32 s100, s100, s33
	s_add_i32 s101, s101, s92
	s_cmpk_lt_i32 s100, 0x600
	s_cselect_b32 s100, s100, s9
	s_cselect_b32 s101, s101, s8
	s_ashr_i32 s0, s100, 31
	s_lshr_b32 s0, s0, 27
	s_add_i32 s0, s100, s0
	s_ashr_i32 s0, s0, 5
	s_lshl_b32 s10, s0, 6
	s_lshl_b32 s1, s0, 11
	v_or_b32_e32 v17, s10, v10
	s_sub_i32 s11, 0, s1
	v_cmp_gt_i32_e32 vcc, s34, v17
	v_mov_b32_e32 v208, 0
	v_mov_b32_e32 v209, 0
	v_mov_b32_e32 v210, 0
	v_mov_b32_e32 v211, 0
	v_mov_b32_e32 v212, 0
	v_mov_b32_e32 v213, 0
	v_mov_b32_e32 v214, 0
	v_mov_b32_e32 v215, 0
	s_and_saveexec_b64 s[0:1], vcc
	s_movk_i32 s12, 0x800
	v_cmp_gt_i32_e32 vcc, s12, v17
	v_mov_b32_e32 v116, 0x200
	v_readlane_b32 s36, v250, 26
	v_cndmask_b32_e64 v116, v116, 0, vcc
	v_add_u32_e32 v116, v116, v17
	v_ashrrev_i32_e32 v117, 31, v116
	v_readlane_b32 s44, v250, 34
	v_readlane_b32 s45, v250, 35
	s_add_i32 s14, s11, s101
	v_add_u32_e32 v118, s14, v12
	v_lshl_add_u64 v[116:117], v[116:117], 2, s[44:45]
	v_add_u32_e32 v122, s14, v13
	v_mad_i64_i32 v[118:119], s[12:13], v118, s22, v[116:117]
	v_mad_i64_i32 v[116:117], s[12:13], v122, s22, v[116:117]
	global_load_dwordx4 v[208:211], v[118:119], off
	s_nop 0
	global_load_dwordx4 v[212:215], v[116:117], off
	v_readlane_b32 s42, v250, 32
	v_readlane_b32 s43, v250, 33
	v_readlane_b32 s42, v254, 30
	v_readlane_b32 s37, v250, 27
	v_readlane_b32 s38, v250, 28
	v_readlane_b32 s39, v250, 29
	v_readlane_b32 s40, v250, 30
	v_readlane_b32 s41, v250, 31
	v_readlane_b32 s46, v250, 36
	v_readlane_b32 s47, v250, 37
	v_readlane_b32 s48, v250, 38
	v_readlane_b32 s49, v250, 39
	v_readlane_b32 s50, v250, 40
	v_readlane_b32 s51, v250, 41
	v_readlane_b32 s43, v254, 31
	s_or_b64 exec, exec, s[0:1]
	s_ashr_i32 s0, s9, 31
	s_lshr_b32 s0, s0, 27
	s_add_i32 s0, s9, s0
	s_ashr_i32 s0, s0, 5
	s_lshl_b32 s10, s0, 6
	s_lshl_b32 s1, s0, 11
	v_or_b32_e32 v17, s10, v10
	s_sub_i32 s11, 0, s1
	v_cmp_gt_i32_e32 vcc, s34, v17
	s_waitcnt lgkmcnt(0)
	s_barrier
;     ...
;   for (int t = blockIdx.x; t < ntk * ntn; t += gridDim.x) {
;     const int tk = t % ntk, tn = t / ntk, k0 = tk * 64, n0 = tn * 64;
;     __syncthreads();
; #pragma unroll
;     for (int i = 0; i < 2; ++i) {
;       const int id = tid + 512 * i, kr = id >> 4, n4 = (id & 15) * 4;
;       f32x4 v = {0.f, 0.f, 0.f, 0.f};
;       const int nd = n0 + n4, nsrc = (nvalid < 0) ? nd : (nd < csplit ? nd + coff1 : nd + coff2);
;       if (nd < ((nvalid < 0) ? N : nvalid)) v = *(const f32x4*)(W + (size_t)(k0 + kr) * N + nsrc);
;       tile[kr * 65 + n4 + 0] = v[0]; tile[kr * 65 + n4 + 1] = v[1]; tile[kr * 65 + n4 + 2] = v[2]; tile[kr * 65 + n4 + 3] = v[3];
;     }
;     __syncthreads();
;     {
;       const int n = tid >> 3, c = tid & 7;
;       bool rot = false;
;       if (PERM == 1) rot = (n0 == rot_n0);
;       if (PERM == 2) rot = ((tn % 3) == 2);
;       const int ns = rot ? ((n >> 1) + 32 * (n & 1)) : n;
;       if (FP8) {
;         float f[8];
; #pragma unroll
;         for (int j = 0; j < 8; ++j) f[j] = tile[(c * 8 + j) * 65 + ns] * wscale;
;         u32x2 o = {pk4_fp8(f[0], f[1], f[2], f[3]), pk4_fp8(f[4], f[5], f[6], f[7])};
;         *(u32x2*)((unsigned char*)Wt + (size_t)(n0 + n) * K + k0 + c * 8) = o;
;       } else {
;         u32x4 o;
; #pragma unroll
;         for (int j = 0; j < 4; ++j) o[j] = pk2(tile[(c * 8 + 2 * j) * 65 + ns], tile[(c * 8 + 2 * j + 1) * 65 + ns]);
;         *(u32x4*)(Wt + (size_t)(n0 + n) * K + k0 + c * 8) = o;
;       }
;     }
	s_waitcnt vmcnt(4)
	ds_write2_b32 v14, v98, v99 offset1:1
	ds_write2_b32 v14, v100, v101 offset0:2 offset1:3
	ds_write2_b32 v15, v102, v103 offset1:1
	ds_write2_b32 v15, v104, v105 offset0:2 offset1:3
	s_waitcnt lgkmcnt(0)
	s_barrier
	ds_read2_b32 v[2:3], v16 offset1:65
	ds_read2_b32 v[4:5], v16 offset0:130 offset1:195
	s_add_i32 s0, s8, s11
	s_ashr_i32 s1, s0, 31
	s_add_i32 s9, s9, s33
	s_waitcnt lgkmcnt(1)
	v_mul_f32_e32 v8, 0x43800000, v2
	v_add_u32_e32 v2, 0x400, v16
	ds_read2_b32 v[6:7], v2 offset0:4 offset1:69
	v_mul_f32_e32 v9, 0x43800000, v3
	ds_read2_b32 v[2:3], v2 offset0:134 offset1:199
	s_waitcnt lgkmcnt(2)
	v_mul_f32_e32 v4, 0x43800000, v4
	v_mul_f32_e32 v5, 0x43800000, v5
	s_waitcnt lgkmcnt(1)
	v_mul_f32_e32 v6, 0x43800000, v6
	v_mul_f32_e32 v7, 0x43800000, v7
	s_waitcnt lgkmcnt(0)
	v_mul_f32_e32 v17, 0x43800000, v2
	v_mul_f32_e32 v18, 0x43800000, v3
	v_med3_f32 v3, v8, s93, v223
	v_med3_f32 v8, v9, s93, v223
	v_mov_b32_e32 v2, v1
	v_cvt_pk_fp8_f32 v2, v3, v8
	v_med3_f32 v6, v6, s93, v223
	v_med3_f32 v7, v7, s93, v223
	v_mov_b32_e32 v3, v1
	v_cvt_pk_fp8_f32 v3, v6, v7
	v_med3_f32 v4, v4, s93, v223
	v_med3_f32 v5, v5, s93, v223
	v_cvt_pk_fp8_f32 v2, v4, v5 op_sel:[0,0,1]
	v_med3_f32 v4, v17, s93, v223
	v_med3_f32 v5, v18, s93, v223
	v_cvt_pk_fp8_f32 v3, v4, v5 op_sel:[0,0,1]
	v_add_u32_e32 v4, s10, v11
	v_ashrrev_i32_e32 v5, 31, v4
	v_lshlrev_b64 v[4:5], 11, v[4:5]
	v_lshl_add_u64 v[4:5], s[6:7], 0, v[4:5]
	v_lshl_add_u64 v[4:5], v[4:5], 0, s[0:1]
	s_add_i32 s8, s8, s92
	v_lshl_add_u64 v[4:5], v[4:5], 0, v[0:1]
	s_cmpk_gt_i32 s9, 0x5ff
	global_store_dwordx2 v[4:5], v[2:3], off
	s_cbranch_scc1 .Lcw4_x1
	s_ashr_i32 s0, s9, 31
	s_lshr_b32 s0, s0, 27
	s_add_i32 s0, s9, s0
	s_ashr_i32 s0, s0, 5
	s_lshl_b32 s10, s0, 6
	s_lshl_b32 s1, s0, 11
	v_or_b32_e32 v17, s10, v10
	s_sub_i32 s11, 0, s1
	v_cmp_gt_i32_e32 vcc, s34, v17
	s_waitcnt lgkmcnt(0)
	s_barrier
	s_waitcnt vmcnt(3)
	ds_write2_b32 v14, v106, v107 offset1:1
	ds_write2_b32 v14, v108, v109 offset0:2 offset1:3
	ds_write2_b32 v15, v110, v111 offset1:1
	ds_write2_b32 v15, v112, v113 offset0:2 offset1:3
	s_waitcnt lgkmcnt(0)
	s_barrier
	ds_read2_b32 v[2:3], v16 offset1:65
	ds_read2_b32 v[4:5], v16 offset0:130 offset1:195
	s_add_i32 s0, s8, s11
	s_ashr_i32 s1, s0, 31
	s_add_i32 s9, s9, s33
	s_waitcnt lgkmcnt(1)
	v_mul_f32_e32 v8, 0x43800000, v2
	v_add_u32_e32 v2, 0x400, v16
	ds_read2_b32 v[6:7], v2 offset0:4 offset1:69
	v_mul_f32_e32 v9, 0x43800000, v3
	ds_read2_b32 v[2:3], v2 offset0:134 offset1:199
	s_waitcnt lgkmcnt(2)
	v_mul_f32_e32 v4, 0x43800000, v4
	v_mul_f32_e32 v5, 0x43800000, v5
	s_waitcnt lgkmcnt(1)
	v_mul_f32_e32 v6, 0x43800000, v6
	v_mul_f32_e32 v7, 0x43800000, v7
	s_waitcnt lgkmcnt(0)
	v_mul_f32_e32 v17, 0x43800000, v2
	v_mul_f32_e32 v18, 0x43800000, v3
	v_med3_f32 v3, v8, s93, v223
	v_med3_f32 v8, v9, s93, v223
	v_mov_b32_e32 v2, v1
	v_cvt_pk_fp8_f32 v2, v3, v8
	v_med3_f32 v6, v6, s93, v223
	v_med3_f32 v7, v7, s93, v223
	v_mov_b32_e32 v3, v1
	v_cvt_pk_fp8_f32 v3, v6, v7
	v_med3_f32 v4, v4, s93, v223
	v_med3_f32 v5, v5, s93, v223
	v_cvt_pk_fp8_f32 v2, v4, v5 op_sel:[0,0,1]
	v_med3_f32 v4, v17, s93, v223
	v_med3_f32 v5, v18, s93, v223
	v_cvt_pk_fp8_f32 v3, v4, v5 op_sel:[0,0,1]
	v_add_u32_e32 v4, s10, v11
	v_ashrrev_i32_e32 v5, 31, v4
	v_lshlrev_b64 v[4:5], 11, v[4:5]
	v_lshl_add_u64 v[4:5], s[6:7], 0, v[4:5]
	v_lshl_add_u64 v[4:5], v[4:5], 0, s[0:1]
	s_add_i32 s8, s8, s92
	v_lshl_add_u64 v[4:5], v[4:5], 0, v[0:1]
	s_cmpk_gt_i32 s9, 0x5ff
	global_store_dwordx2 v[4:5], v[2:3], off
	s_cbranch_scc1 .Lcw4_x2
	s_ashr_i32 s0, s9, 31
	s_lshr_b32 s0, s0, 27
	s_add_i32 s0, s9, s0
	s_ashr_i32 s0, s0, 5
	s_lshl_b32 s10, s0, 6
	s_lshl_b32 s1, s0, 11
	v_or_b32_e32 v17, s10, v10
	s_sub_i32 s11, 0, s1
	v_cmp_gt_i32_e32 vcc, s34, v17
	s_waitcnt lgkmcnt(0)
	s_barrier
	s_waitcnt vmcnt(2)
	ds_write2_b32 v14, v208, v209 offset1:1
	ds_write2_b32 v14, v210, v211 offset0:2 offset1:3
	ds_write2_b32 v15, v212, v213 offset1:1
	ds_write2_b32 v15, v214, v215 offset0:2 offset1:3
	s_waitcnt lgkmcnt(0)
	s_barrier
	ds_read2_b32 v[2:3], v16 offset1:65
	ds_read2_b32 v[4:5], v16 offset0:130 offset1:195
	s_add_i32 s0, s8, s11
	s_ashr_i32 s1, s0, 31
	s_add_i32 s9, s9, s33
	s_waitcnt lgkmcnt(1)
	v_mul_f32_e32 v8, 0x43800000, v2
	v_add_u32_e32 v2, 0x400, v16
	ds_read2_b32 v[6:7], v2 offset0:4 offset1:69
	v_mul_f32_e32 v9, 0x43800000, v3
	ds_read2_b32 v[2:3], v2 offset0:134 offset1:199
	s_waitcnt lgkmcnt(2)
	v_mul_f32_e32 v4, 0x43800000, v4
	v_mul_f32_e32 v5, 0x43800000, v5
	s_waitcnt lgkmcnt(1)
	v_mul_f32_e32 v6, 0x43800000, v6
	v_mul_f32_e32 v7, 0x43800000, v7
	s_waitcnt lgkmcnt(0)
	v_mul_f32_e32 v17, 0x43800000, v2
	v_mul_f32_e32 v18, 0x43800000, v3
	v_med3_f32 v3, v8, s93, v223
	v_med3_f32 v8, v9, s93, v223
	v_mov_b32_e32 v2, v1
	v_cvt_pk_fp8_f32 v2, v3, v8
	v_med3_f32 v6, v6, s93, v223
	v_med3_f32 v7, v7, s93, v223
	v_mov_b32_e32 v3, v1
	v_cvt_pk_fp8_f32 v3, v6, v7
	v_med3_f32 v4, v4, s93, v223
	v_med3_f32 v5, v5, s93, v223
	v_cvt_pk_fp8_f32 v2, v4, v5 op_sel:[0,0,1]
	v_med3_f32 v4, v17, s93, v223
	v_med3_f32 v5, v18, s93, v223
	v_cvt_pk_fp8_f32 v3, v4, v5 op_sel:[0,0,1]
	v_add_u32_e32 v4, s10, v11
	v_ashrrev_i32_e32 v5, 31, v4
	v_lshlrev_b64 v[4:5], 11, v[4:5]
	v_lshl_add_u64 v[4:5], s[6:7], 0, v[4:5]
	v_lshl_add_u64 v[4:5], v[4:5], 0, s[0:1]
	s_add_i32 s8, s8, s92
	v_lshl_add_u64 v[4:5], v[4:5], 0, v[0:1]
	s_cmpk_gt_i32 s9, 0x5ff
	global_store_dwordx2 v[4:5], v[2:3], off
	s_cbranch_scc1 .LBB0_1455
	s_branch .Lcw4_top

;     ...
;   for (int t = blockIdx.x; t < ntk * ntn; t += gridDim.x) {
;     const int tk = t % ntk, tn = t / ntk, k0 = tk * 64, n0 = tn * 64;
;     __syncthreads();
; #pragma unroll
;     for (int i = 0; i < 2; ++i) {
;       const int id = tid + 512 * i, kr = id >> 4, n4 = (id & 15) * 4;
;       f32x4 v = {0.f, 0.f, 0.f, 0.f};
;       const int nd = n0 + n4, nsrc = (nvalid < 0) ? nd : (nd < csplit ? nd + coff1 : nd + coff2);
;       if (nd < ((nvalid < 0) ? N : nvalid)) v = *(const f32x4*)(W + (size_t)(k0 + kr) * N + nsrc);
;       tile[kr * 65 + n4 + 0] = v[0]; tile[kr * 65 + n4 + 1] = v[1]; tile[kr * 65 + n4 + 2] = v[2]; tile[kr * 65 + n4 + 3] = v[3];
;     }
;     __syncthreads();
;     {
;       const int n = tid >> 3, c = tid & 7;
;       bool rot = false;
;       if (PERM == 1) rot = (n0 == rot_n0);
;       if (PERM == 2) rot = ((tn % 3) == 2);
;       const int ns = rot ? ((n >> 1) + 32 * (n & 1)) : n;
;       if (FP8) {
;         float f[8];
; #pragma unroll
;         for (int j = 0; j < 8; ++j) f[j] = tile[(c * 8 + j) * 65 + ns] * wscale;
;         u32x2 o = {pk4_fp8(f[0], f[1], f[2], f[3]), pk4_fp8(f[4], f[5], f[6], f[7])};
;         *(u32x2*)((unsigned char*)Wt + (size_t)(n0 + n) * K + k0 + c * 8) = o;
;       } else {
;         u32x4 o;
; #pragma unroll
;         for (int j = 0; j < 4; ++j) o[j] = pk2(tile[(c * 8 + 2 * j) * 65 + ns], tile[(c * 8 + 2 * j + 1) * 65 + ns]);
;         *(u32x4*)(Wt + (size_t)(n0 + n) * K + k0 + c * 8) = o;
;       }
;     }
.Lcw5_top:
	s_mov_b32 s100, s11
	s_mov_b32 s101, s10
	s_ashr_i32 s8, s100, 31
	s_lshr_b32 s8, s8, 27
	s_add_i32 s8, s100, s8
	s_ashr_i32 s8, s8, 5
	s_lshl_b32 s12, s8, 6
	s_lshl_b32 s9, s8, 11
	v_or_b32_e32 v18, s12, v10
	s_movk_i32 s8, 0xe40
	s_sub_i32 s13, 0, s9
	v_cmp_gt_i32_e32 vcc, s8, v18
	v_mov_b32_e32 v98, 0
	v_mov_b32_e32 v99, 0
	v_mov_b32_e32 v100, 0
	v_mov_b32_e32 v101, 0
	v_mov_b32_e32 v102, 0
	v_mov_b32_e32 v103, 0
	v_mov_b32_e32 v104, 0
	v_mov_b32_e32 v105, 0
	s_and_saveexec_b64 s[8:9], vcc
	s_movk_i32 s14, 0x240
	v_cmp_gt_i32_e32 vcc, s14, v18
	s_add_i32 s16, s13, s101
	v_add_u32_e32 v118, s16, v12
	v_cndmask_b32_e32 v116, v224, v225, vcc
	v_add_u32_e32 v116, v116, v18
	v_ashrrev_i32_e32 v117, 31, v116
	v_lshl_add_u64 v[116:117], v[116:117], 2, s[0:1]
	s_movk_i32 s17, 0x6100
	v_add_u32_e32 v122, s16, v14
	v_mad_i64_i32 v[118:119], s[14:15], v118, s17, v[116:117]
	v_mad_i64_i32 v[116:117], s[14:15], v122, s17, v[116:117]
	global_load_dwordx4 v[98:101], v[118:119], off
	s_nop 0
	global_load_dwordx4 v[102:105], v[116:117], off
	s_or_b64 exec, exec, s[8:9]
	s_add_i32 s100, s100, s33
	s_add_i32 s101, s101, s92
	s_cmpk_lt_i32 s100, 0x780
	s_cselect_b32 s100, s100, s11
	s_cselect_b32 s101, s101, s10
	s_ashr_i32 s8, s100, 31
	s_lshr_b32 s8, s8, 27
	s_add_i32 s8, s100, s8
	s_ashr_i32 s8, s8, 5
	s_lshl_b32 s12, s8, 6
	s_lshl_b32 s9, s8, 11
	v_or_b32_e32 v18, s12, v10
	s_movk_i32 s8, 0xe40
	s_sub_i32 s13, 0, s9
	v_cmp_gt_i32_e32 vcc, s8, v18
	v_mov_b32_e32 v106, 0
	v_mov_b32_e32 v107, 0
	v_mov_b32_e32 v108, 0
	v_mov_b32_e32 v109, 0
	v_mov_b32_e32 v110, 0
	v_mov_b32_e32 v111, 0
	v_mov_b32_e32 v112, 0
	v_mov_b32_e32 v113, 0
	s_and_saveexec_b64 s[8:9], vcc
	s_movk_i32 s14, 0x240
	v_cmp_gt_i32_e32 vcc, s14, v18
	s_add_i32 s16, s13, s101
	v_add_u32_e32 v118, s16, v12
	v_cndmask_b32_e32 v116, v224, v225, vcc
	v_add_u32_e32 v116, v116, v18
	v_ashrrev_i32_e32 v117, 31, v116
	v_lshl_add_u64 v[116:117], v[116:117], 2, s[0:1]
	s_movk_i32 s17, 0x6100
	v_add_u32_e32 v122, s16, v14
	v_mad_i64_i32 v[118:119], s[14:15], v118, s17, v[116:117]
	v_mad_i64_i32 v[116:117], s[14:15], v122, s17, v[116:117]
	global_load_dwordx4 v[106:109], v[118:119], off
	s_nop 0
	global_load_dwordx4 v[110:113], v[116:117], off
	s_or_b64 exec, exec, s[8:9]
	s_add_i32 s100, s100, s33
	s_add_i32 s101, s101, s92
	s_cmpk_lt_i32 s100, 0x780
	s_cselect_b32 s100, s100, s11
	s_cselect_b32 s101, s101, s10
	s_ashr_i32 s8, s100, 31
	s_lshr_b32 s8, s8, 27
	s_add_i32 s8, s100, s8
	s_ashr_i32 s8, s8, 5
	s_lshl_b32 s12, s8, 6
	s_lshl_b32 s9, s8, 11
	v_or_b32_e32 v18, s12, v10
	s_movk_i32 s8, 0xe40
	s_sub_i32 s13, 0, s9
	v_cmp_gt_i32_e32 vcc, s8, v18
	v_mov_b32_e32 v208, 0
	v_mov_b32_e32 v209, 0
	v_mov_b32_e32 v210, 0
	v_mov_b32_e32 v211, 0
	v_mov_b32_e32 v212, 0
	v_mov_b32_e32 v213, 0
	v_mov_b32_e32 v214, 0
	v_mov_b32_e32 v215, 0
	s_and_saveexec_b64 s[8:9], vcc
	s_movk_i32 s14, 0x240
	v_cmp_gt_i32_e32 vcc, s14, v18
	s_add_i32 s16, s13, s101
	v_add_u32_e32 v118, s16, v12
	v_cndmask_b32_e32 v116, v224, v225, vcc
	v_add_u32_e32 v116, v116, v18
	v_ashrrev_i32_e32 v117, 31, v116
	v_lshl_add_u64 v[116:117], v[116:117], 2, s[0:1]
	s_movk_i32 s17, 0x6100
	v_add_u32_e32 v122, s16, v14
	v_mad_i64_i32 v[118:119], s[14:15], v118, s17, v[116:117]
	v_mad_i64_i32 v[116:117], s[14:15], v122, s17, v[116:117]
	global_load_dwordx4 v[208:211], v[118:119], off
	s_nop 0
	global_load_dwordx4 v[212:215], v[116:117], off
	s_or_b64 exec, exec, s[8:9]
	s_ashr_i32 s8, s11, 31
	s_lshr_b32 s8, s8, 27
	s_add_i32 s8, s11, s8
	s_ashr_i32 s8, s8, 5
	s_lshl_b32 s12, s8, 6
	s_lshl_b32 s9, s8, 11
	v_or_b32_e32 v18, s12, v10
	s_movk_i32 s8, 0xe40
	s_sub_i32 s13, 0, s9
	v_cmp_gt_i32_e32 vcc, s8, v18
	s_waitcnt lgkmcnt(0)
	s_barrier
	s_add_i32 s8, s10, s13
	s_and_b32 s9, s11, 0xffffffe0
	s_cmpk_eq_i32 s9, 0x100
	s_cselect_b64 vcc, -1, 0
	s_waitcnt vmcnt(4)
	ds_write2_b32 v16, v98, v99 offset1:1
	ds_write2_b32 v16, v100, v101 offset0:2 offset1:3
	ds_write2_b32 v17, v102, v103 offset1:1
	ds_write2_b32 v17, v104, v105 offset0:2 offset1:3
	v_cndmask_b32_e32 v2, v11, v13, vcc
	v_lshl_add_u32 v6, v2, 2, v15
	s_waitcnt lgkmcnt(0)
	s_barrier
;     ...
;   for (int t = blockIdx.x; t < ntk * ntn; t += gridDim.x) {
;     const int tk = t % ntk, tn = t / ntk, k0 = tk * 64, n0 = tn * 64;
;     __syncthreads();
; #pragma unroll
;     for (int i = 0; i < 2; ++i) {
;       const int id = tid + 512 * i, kr = id >> 4, n4 = (id & 15) * 4;
;       f32x4 v = {0.f, 0.f, 0.f, 0.f};
;       const int nd = n0 + n4, nsrc = (nvalid < 0) ? nd : (nd < csplit ? nd + coff1 : nd + coff2);
;       if (nd < ((nvalid < 0) ? N : nvalid)) v = *(const f32x4*)(W + (size_t)(k0 + kr) * N + nsrc);
;       tile[kr * 65 + n4 + 0] = v[0]; tile[kr * 65 + n4 + 1] = v[1]; tile[kr * 65 + n4 + 2] = v[2]; tile[kr * 65 + n4 + 3] = v[3];
;     }
;     __syncthreads();
;     {
;       const int n = tid >> 3, c = tid & 7;
;       bool rot = false;
;       if (PERM == 1) rot = (n0 == rot_n0);
;       if (PERM == 2) rot = ((tn % 3) == 2);
;       const int ns = rot ? ((n >> 1) + 32 * (n & 1)) : n;
;       if (FP8) {
;         float f[8];
; #pragma unroll
;         for (int j = 0; j < 8; ++j) f[j] = tile[(c * 8 + j) * 65 + ns] * wscale;
;         u32x2 o = {pk4_fp8(f[0], f[1], f[2], f[3]), pk4_fp8(f[4], f[5], f[6], f[7])};
;         *(u32x2*)((unsigned char*)Wt + (size_t)(n0 + n) * K + k0 + c * 8) = o;
;       } else {
;         u32x4 o;
; #pragma unroll
;         for (int j = 0; j < 4; ++j) o[j] = pk2(tile[(c * 8 + 2 * j) * 65 + ns], tile[(c * 8 + 2 * j + 1) * 65 + ns]);
;         *(u32x4*)(Wt + (size_t)(n0 + n) * K + k0 + c * 8) = o;
;       }
;     }
	ds_read2_b32 v[2:3], v6 offset1:65
	ds_read2_b32 v[4:5], v6 offset0:130 offset1:195
	v_add_u32_e32 v6, 0x400, v6
	s_ashr_i32 s9, s8, 31
	s_add_i32 s11, s11, s33
	s_waitcnt lgkmcnt(1)
	v_cvt_pk_bf16_f32 v2, v2, v3
	s_waitcnt lgkmcnt(0)
	v_cvt_pk_bf16_f32 v3, v4, v5
	ds_read2_b32 v[4:5], v6 offset0:4 offset1:69
	ds_read2_b32 v[6:7], v6 offset0:134 offset1:199
	s_add_i32 s10, s10, s92
	s_cmpk_lt_i32 s11, 0x780
	s_waitcnt lgkmcnt(1)
	v_cvt_pk_bf16_f32 v4, v4, v5
	s_waitcnt lgkmcnt(0)
	v_cvt_pk_bf16_f32 v5, v6, v7
	v_add_u32_e32 v6, s12, v11
	v_ashrrev_i32_e32 v7, 31, v6
	v_readlane_b32 s12, v253, 15
	v_lshlrev_b64 v[6:7], 12, v[6:7]
	v_readlane_b32 s13, v253, 16
	s_nop 1
	v_lshl_add_u64 v[6:7], s[12:13], 0, v[6:7]
	v_lshl_add_u64 v[6:7], s[8:9], 1, v[6:7]
	v_lshl_add_u64 v[6:7], v[6:7], 0, v[0:1]
	global_store_dwordx4 v[6:7], v[2:5], off
	s_cbranch_scc0 .Lcw5_x1
	s_ashr_i32 s8, s11, 31
	s_lshr_b32 s8, s8, 27
	s_add_i32 s8, s11, s8
	s_ashr_i32 s8, s8, 5
	s_lshl_b32 s12, s8, 6
	s_lshl_b32 s9, s8, 11
	v_or_b32_e32 v18, s12, v10
	s_movk_i32 s8, 0xe40
	s_sub_i32 s13, 0, s9
	v_cmp_gt_i32_e32 vcc, s8, v18
	s_waitcnt lgkmcnt(0)
	s_barrier
	s_add_i32 s8, s10, s13
	s_and_b32 s9, s11, 0xffffffe0
	s_cmpk_eq_i32 s9, 0x100
	s_cselect_b64 vcc, -1, 0
	s_waitcnt vmcnt(3)
	ds_write2_b32 v16, v106, v107 offset1:1
	ds_write2_b32 v16, v108, v109 offset0:2 offset1:3
	ds_write2_b32 v17, v110, v111 offset1:1
	ds_write2_b32 v17, v112, v113 offset0:2 offset1:3
	v_cndmask_b32_e32 v2, v11, v13, vcc
	v_lshl_add_u32 v6, v2, 2, v15
	s_waitcnt lgkmcnt(0)
	s_barrier
	ds_read2_b32 v[2:3], v6 offset1:65
	ds_read2_b32 v[4:5], v6 offset0:130 offset1:195
	v_add_u32_e32 v6, 0x400, v6
	s_ashr_i32 s9, s8, 31
	s_add_i32 s11, s11, s33
	s_waitcnt lgkmcnt(1)
	v_cvt_pk_bf16_f32 v2, v2, v3
	s_waitcnt lgkmcnt(0)
	v_cvt_pk_bf16_f32 v3, v4, v5
	ds_read2_b32 v[4:5], v6 offset0:4 offset1:69
	ds_read2_b32 v[6:7], v6 offset0:134 offset1:199
	s_add_i32 s10, s10, s92
	s_cmpk_lt_i32 s11, 0x780
	s_waitcnt lgkmcnt(1)
	v_cvt_pk_bf16_f32 v4, v4, v5
	s_waitcnt lgkmcnt(0)
	v_cvt_pk_bf16_f32 v5, v6, v7
	v_add_u32_e32 v6, s12, v11
	v_ashrrev_i32_e32 v7, 31, v6
	v_readlane_b32 s12, v253, 15
	v_lshlrev_b64 v[6:7], 12, v[6:7]
	v_readlane_b32 s13, v253, 16
	s_nop 1
	v_lshl_add_u64 v[6:7], s[12:13], 0, v[6:7]
	v_lshl_add_u64 v[6:7], s[8:9], 1, v[6:7]
	v_lshl_add_u64 v[6:7], v[6:7], 0, v[0:1]
	global_store_dwordx4 v[6:7], v[2:5], off
	s_cbranch_scc0 .Lcw5_x2
	s_ashr_i32 s8, s11, 31
	s_lshr_b32 s8, s8, 27
	s_add_i32 s8, s11, s8
	s_ashr_i32 s8, s8, 5
	s_lshl_b32 s12, s8, 6
	s_lshl_b32 s9, s8, 11
	v_or_b32_e32 v18, s12, v10
	s_movk_i32 s8, 0xe40
	s_sub_i32 s13, 0, s9
	v_cmp_gt_i32_e32 vcc, s8, v18
	s_waitcnt lgkmcnt(0)
	s_barrier
	s_add_i32 s8, s10, s13
	s_and_b32 s9, s11, 0xffffffe0
	s_cmpk_eq_i32 s9, 0x100
	s_cselect_b64 vcc, -1, 0
	s_waitcnt vmcnt(2)
	ds_write2_b32 v16, v208, v209 offset1:1
	ds_write2_b32 v16, v210, v211 offset0:2 offset1:3
	ds_write2_b32 v17, v212, v213 offset1:1
	ds_write2_b32 v17, v214, v215 offset0:2 offset1:3
	v_cndmask_b32_e32 v2, v11, v13, vcc
	v_lshl_add_u32 v6, v2, 2, v15
	s_waitcnt lgkmcnt(0)
	s_barrier
	ds_read2_b32 v[2:3], v6 offset1:65
	ds_read2_b32 v[4:5], v6 offset0:130 offset1:195
	v_add_u32_e32 v6, 0x400, v6
	s_ashr_i32 s9, s8, 31
	s_add_i32 s11, s11, s33
	s_waitcnt lgkmcnt(1)
	v_cvt_pk_bf16_f32 v2, v2, v3
	s_waitcnt lgkmcnt(0)
	v_cvt_pk_bf16_f32 v3, v4, v5
	ds_read2_b32 v[4:5], v6 offset0:4 offset1:69
	ds_read2_b32 v[6:7], v6 offset0:134 offset1:199
	s_add_i32 s10, s10, s92
	s_cmpk_lt_i32 s11, 0x780
	s_waitcnt lgkmcnt(1)
	v_cvt_pk_bf16_f32 v4, v4, v5
	s_waitcnt lgkmcnt(0)
	v_cvt_pk_bf16_f32 v5, v6, v7
	v_add_u32_e32 v6, s12, v11
	v_ashrrev_i32_e32 v7, 31, v6
	v_readlane_b32 s12, v253, 15
	v_lshlrev_b64 v[6:7], 12, v[6:7]
	v_readlane_b32 s13, v253, 16
	s_nop 1
	v_lshl_add_u64 v[6:7], s[12:13], 0, v[6:7]
	v_lshl_add_u64 v[6:7], s[8:9], 1, v[6:7]
	v_lshl_add_u64 v[6:7], v[6:7], 0, v[0:1]
	global_store_dwordx4 v[6:7], v[2:5], off
	s_cbranch_scc0 .LBB0_1461
	s_branch .Lcw5_top

;     ...
;   for (int t = blockIdx.x; t < ntk * ntn; t += gridDim.x) {
;     const int tk = t % ntk, tn = t / ntk, k0 = tk * 64, n0 = tn * 64;
;     __syncthreads();
; #pragma unroll
;     for (int i = 0; i < 2; ++i) {
;       const int id = tid + 512 * i, kr = id >> 4, n4 = (id & 15) * 4;
;       f32x4 v = {0.f, 0.f, 0.f, 0.f};
;       const int nd = n0 + n4, nsrc = (nvalid < 0) ? nd : (nd < csplit ? nd + coff1 : nd + coff2);
;       if (nd < ((nvalid < 0) ? N : nvalid)) v = *(const f32x4*)(W + (size_t)(k0 + kr) * N + nsrc);
;       tile[kr * 65 + n4 + 0] = v[0]; tile[kr * 65 + n4 + 1] = v[1]; tile[kr * 65 + n4 + 2] = v[2]; tile[kr * 65 + n4 + 3] = v[3];
;     }
;     __syncthreads();
;     {
;       const int n = tid >> 3, c = tid & 7;
;       bool rot = false;
;       if (PERM == 1) rot = (n0 == rot_n0);
;       if (PERM == 2) rot = ((tn % 3) == 2);
;       const int ns = rot ? ((n >> 1) + 32 * (n & 1)) : n;
;       if (FP8) {
;         float f[8];
; #pragma unroll
;         for (int j = 0; j < 8; ++j) f[j] = tile[(c * 8 + j) * 65 + ns] * wscale;
;         u32x2 o = {pk4_fp8(f[0], f[1], f[2], f[3]), pk4_fp8(f[4], f[5], f[6], f[7])};
;         *(u32x2*)((unsigned char*)Wt + (size_t)(n0 + n) * K + k0 + c * 8) = o;
;       } else {
;         u32x4 o;
; #pragma unroll
;         for (int j = 0; j < 4; ++j) o[j] = pk2(tile[(c * 8 + 2 * j) * 65 + ns], tile[(c * 8 + 2 * j + 1) * 65 + ns]);
;         *(u32x4*)(Wt + (size_t)(n0 + n) * K + k0 + c * 8) = o;
;       }
;     }
.Lcw6_top:
	s_mov_b32 s100, s11
	s_mov_b32 s101, s10
	s_ashr_i32 s8, s100, 31
	s_lshr_b32 s8, s8, 27
	s_add_i32 s8, s100, s8
	s_ashr_i32 s8, s8, 5
	s_lshl_b32 s12, s8, 6
	s_lshl_b32 s9, s8, 11
	v_or_b32_e32 v17, s12, v10
	s_movk_i32 s8, 0xa00
	s_sub_i32 s13, 0, s9
	v_cmp_gt_i32_e32 vcc, s8, v17
	v_mov_b32_e32 v98, 0
	v_mov_b32_e32 v99, 0
	v_mov_b32_e32 v100, 0
	v_mov_b32_e32 v101, 0
	v_mov_b32_e32 v102, 0
	v_mov_b32_e32 v103, 0
	v_mov_b32_e32 v104, 0
	v_mov_b32_e32 v105, 0
	s_and_saveexec_b64 s[8:9], vcc
	v_cmp_gt_i32_e32 vcc, s20, v17
	s_add_i32 s16, s13, s101
	v_add_u32_e32 v118, s16, v12
	v_cndmask_b32_e64 v116, v226, 0, vcc
	v_add_u32_e32 v116, v116, v17
	v_ashrrev_i32_e32 v117, 31, v116
	v_lshl_add_u64 v[116:117], v[116:117], 2, s[0:1]
	s_movk_i32 s17, 0x6100
	v_add_u32_e32 v122, s16, v13
	v_mad_i64_i32 v[118:119], s[14:15], v118, s17, v[116:117]
	v_mad_i64_i32 v[116:117], s[14:15], v122, s17, v[116:117]
	global_load_dwordx4 v[98:101], v[118:119], off
	s_nop 0
	global_load_dwordx4 v[102:105], v[116:117], off
	s_or_b64 exec, exec, s[8:9]
	s_add_i32 s100, s100, s33
	s_add_i32 s101, s101, s92
	s_cmpk_lt_i32 s100, 0x500
	s_cselect_b32 s100, s100, s11
	s_cselect_b32 s101, s101, s10
	s_ashr_i32 s8, s100, 31
	s_lshr_b32 s8, s8, 27
	s_add_i32 s8, s100, s8
	s_ashr_i32 s8, s8, 5
	s_lshl_b32 s12, s8, 6
	s_lshl_b32 s9, s8, 11
	v_or_b32_e32 v17, s12, v10
	s_movk_i32 s8, 0xa00
	s_sub_i32 s13, 0, s9
	v_cmp_gt_i32_e32 vcc, s8, v17
	v_mov_b32_e32 v106, 0
	v_mov_b32_e32 v107, 0
	v_mov_b32_e32 v108, 0
	v_mov_b32_e32 v109, 0
	v_mov_b32_e32 v110, 0
	v_mov_b32_e32 v111, 0
	v_mov_b32_e32 v112, 0
	v_mov_b32_e32 v113, 0
	s_and_saveexec_b64 s[8:9], vcc
	v_cmp_gt_i32_e32 vcc, s20, v17
	s_add_i32 s16, s13, s101
	v_add_u32_e32 v118, s16, v12
	v_cndmask_b32_e64 v116, v226, 0, vcc
	v_add_u32_e32 v116, v116, v17
	v_ashrrev_i32_e32 v117, 31, v116
	v_lshl_add_u64 v[116:117], v[116:117], 2, s[0:1]
	s_movk_i32 s17, 0x6100
	v_add_u32_e32 v122, s16, v13
	v_mad_i64_i32 v[118:119], s[14:15], v118, s17, v[116:117]
	v_mad_i64_i32 v[116:117], s[14:15], v122, s17, v[116:117]
	global_load_dwordx4 v[106:109], v[118:119], off
	s_nop 0
	global_load_dwordx4 v[110:113], v[116:117], off
	s_or_b64 exec, exec, s[8:9]
	s_add_i32 s100, s100, s33
	s_add_i32 s101, s101, s92
	s_cmpk_lt_i32 s100, 0x500
	s_cselect_b32 s100, s100, s11
	s_cselect_b32 s101, s101, s10
	s_ashr_i32 s8, s100, 31
	s_lshr_b32 s8, s8, 27
	s_add_i32 s8, s100, s8
	s_ashr_i32 s8, s8, 5
	s_lshl_b32 s12, s8, 6
	s_lshl_b32 s9, s8, 11
	v_or_b32_e32 v17, s12, v10
	s_movk_i32 s8, 0xa00
	s_sub_i32 s13, 0, s9
	v_cmp_gt_i32_e32 vcc, s8, v17
	v_mov_b32_e32 v208, 0
	v_mov_b32_e32 v209, 0
	v_mov_b32_e32 v210, 0
	v_mov_b32_e32 v211, 0
	v_mov_b32_e32 v212, 0
	v_mov_b32_e32 v213, 0
	v_mov_b32_e32 v214, 0
	v_mov_b32_e32 v215, 0
	s_and_saveexec_b64 s[8:9], vcc
	v_cmp_gt_i32_e32 vcc, s20, v17
	s_add_i32 s16, s13, s101
	v_add_u32_e32 v118, s16, v12
	v_cndmask_b32_e64 v116, v226, 0, vcc
	v_add_u32_e32 v116, v116, v17
	v_ashrrev_i32_e32 v117, 31, v116
	v_lshl_add_u64 v[116:117], v[116:117], 2, s[0:1]
	s_movk_i32 s17, 0x6100
	v_add_u32_e32 v122, s16, v13
	v_mad_i64_i32 v[118:119], s[14:15], v118, s17, v[116:117]
	v_mad_i64_i32 v[116:117], s[14:15], v122, s17, v[116:117]
	global_load_dwordx4 v[208:211], v[118:119], off
	s_nop 0
	global_load_dwordx4 v[212:215], v[116:117], off
	s_or_b64 exec, exec, s[8:9]
	s_ashr_i32 s8, s11, 31
	s_lshr_b32 s8, s8, 27
	s_add_i32 s8, s11, s8
	s_ashr_i32 s8, s8, 5
	s_lshl_b32 s12, s8, 6
	s_lshl_b32 s9, s8, 11
	v_or_b32_e32 v17, s12, v10
	s_movk_i32 s8, 0xa00
	s_sub_i32 s13, 0, s9
	v_cmp_gt_i32_e32 vcc, s8, v17
	s_waitcnt lgkmcnt(0)
	s_barrier
	s_waitcnt vmcnt(4)
	ds_write2_b32 v14, v98, v99 offset1:1
	ds_write2_b32 v14, v100, v101 offset0:2 offset1:3
	ds_write2_b32 v15, v102, v103 offset1:1
	ds_write2_b32 v15, v104, v105 offset0:2 offset1:3
	s_waitcnt lgkmcnt(0)
	s_barrier
	ds_read2_b32 v[2:3], v16 offset1:65
	ds_read2_b32 v[4:5], v16 offset0:130 offset1:195
	s_add_i32 s8, s10, s13
	s_ashr_i32 s9, s8, 31
	s_add_i32 s11, s11, s33
	s_waitcnt lgkmcnt(1)
	v_mul_f32_e32 v8, 0x43800000, v2
	v_add_u32_e32 v2, 0x400, v16
	ds_read2_b32 v[6:7], v2 offset0:4 offset1:69
	v_mul_f32_e32 v9, 0x43800000, v3
	ds_read2_b32 v[2:3], v2 offset0:134 offset1:199
	s_waitcnt lgkmcnt(2)
	v_mul_f32_e32 v4, 0x43800000, v4
	v_mul_f32_e32 v5, 0x43800000, v5
	s_waitcnt lgkmcnt(1)
	v_mul_f32_e32 v6, 0x43800000, v6
	v_mul_f32_e32 v7, 0x43800000, v7
	s_waitcnt lgkmcnt(0)
	v_mul_f32_e32 v17, 0x43800000, v2
	v_mul_f32_e32 v18, 0x43800000, v3
	v_med3_f32 v3, v8, s93, v223
	v_med3_f32 v8, v9, s93, v223
	v_mov_b32_e32 v2, v1
	v_cvt_pk_fp8_f32 v2, v3, v8
	v_med3_f32 v6, v6, s93, v223
	v_med3_f32 v7, v7, s93, v223
	v_mov_b32_e32 v3, v1
	v_cvt_pk_fp8_f32 v3, v6, v7
	v_med3_f32 v4, v4, s93, v223
	v_med3_f32 v5, v5, s93, v223
	v_cvt_pk_fp8_f32 v2, v4, v5 op_sel:[0,0,1]
	v_med3_f32 v4, v17, s93, v223
	v_med3_f32 v5, v18, s93, v223
	v_cvt_pk_fp8_f32 v3, v4, v5 op_sel:[0,0,1]
	v_add_u32_e32 v4, s12, v11
	v_ashrrev_i32_e32 v5, 31, v4
	v_lshlrev_b64 v[4:5], 11, v[4:5]
	v_lshl_add_u64 v[4:5], s[6:7], 0, v[4:5]
	v_lshl_add_u64 v[4:5], v[4:5], 0, s[8:9]
	s_add_i32 s10, s10, s92
	v_lshl_add_u64 v[4:5], v[4:5], 0, v[0:1]
	s_cmpk_lt_i32 s11, 0x500
	global_store_dwordx2 v[4:5], v[2:3], off
	s_cbranch_scc0 .Lcw6_x1
;     ...
;   for (int t = blockIdx.x; t < ntk * ntn; t += gridDim.x) {
;     const int tk = t % ntk, tn = t / ntk, k0 = tk * 64, n0 = tn * 64;
;     __syncthreads();
; #pragma unroll
;     for (int i = 0; i < 2; ++i) {
;       const int id = tid + 512 * i, kr = id >> 4, n4 = (id & 15) * 4;
;       f32x4 v = {0.f, 0.f, 0.f, 0.f};
;       const int nd = n0 + n4, nsrc = (nvalid < 0) ? nd : (nd < csplit ? nd + coff1 : nd + coff2);
;       if (nd < ((nvalid < 0) ? N : nvalid)) v = *(const f32x4*)(W + (size_t)(k0 + kr) * N + nsrc);
;       tile[kr * 65 + n4 + 0] = v[0]; tile[kr * 65 + n4 + 1] = v[1]; tile[kr * 65 + n4 + 2] = v[2]; tile[kr * 65 + n4 + 3] = v[3];
;     }
;     __syncthreads();
;     {
;       const int n = tid >> 3, c = tid & 7;
;       bool rot = false;
;       if (PERM == 1) rot = (n0 == rot_n0);
;       if (PERM == 2) rot = ((tn % 3) == 2);
;       const int ns = rot ? ((n >> 1) + 32 * (n & 1)) : n;
;       if (FP8) {
;         float f[8];
; #pragma unroll
;         for (int j = 0; j < 8; ++j) f[j] = tile[(c * 8 + j) * 65 + ns] * wscale;
;         u32x2 o = {pk4_fp8(f[0], f[1], f[2], f[3]), pk4_fp8(f[4], f[5], f[6], f[7])};
;         *(u32x2*)((unsigned char*)Wt + (size_t)(n0 + n) * K + k0 + c * 8) = o;
;       } else {
;         u32x4 o;
; #pragma unroll
;         for (int j = 0; j < 4; ++j) o[j] = pk2(tile[(c * 8 + 2 * j) * 65 + ns], tile[(c * 8 + 2 * j + 1) * 65 + ns]);
;         *(u32x4*)(Wt + (size_t)(n0 + n) * K + k0 + c * 8) = o;
;       }
;     }
	s_ashr_i32 s8, s11, 31
	s_lshr_b32 s8, s8, 27
	s_add_i32 s8, s11, s8
	s_ashr_i32 s8, s8, 5
	s_lshl_b32 s12, s8, 6
	s_lshl_b32 s9, s8, 11
	v_or_b32_e32 v17, s12, v10
	s_movk_i32 s8, 0xa00
	s_sub_i32 s13, 0, s9
	v_cmp_gt_i32_e32 vcc, s8, v17
	s_waitcnt lgkmcnt(0)
	s_barrier
	s_waitcnt vmcnt(3)
	ds_write2_b32 v14, v106, v107 offset1:1
	ds_write2_b32 v14, v108, v109 offset0:2 offset1:3
	ds_write2_b32 v15, v110, v111 offset1:1
	ds_write2_b32 v15, v112, v113 offset0:2 offset1:3
	s_waitcnt lgkmcnt(0)
	s_barrier
	ds_read2_b32 v[2:3], v16 offset1:65
	ds_read2_b32 v[4:5], v16 offset0:130 offset1:195
	s_add_i32 s8, s10, s13
	s_ashr_i32 s9, s8, 31
	s_add_i32 s11, s11, s33
	s_waitcnt lgkmcnt(1)
	v_mul_f32_e32 v8, 0x43800000, v2
	v_add_u32_e32 v2, 0x400, v16
	ds_read2_b32 v[6:7], v2 offset0:4 offset1:69
	v_mul_f32_e32 v9, 0x43800000, v3
	ds_read2_b32 v[2:3], v2 offset0:134 offset1:199
	s_waitcnt lgkmcnt(2)
	v_mul_f32_e32 v4, 0x43800000, v4
	v_mul_f32_e32 v5, 0x43800000, v5
	s_waitcnt lgkmcnt(1)
	v_mul_f32_e32 v6, 0x43800000, v6
	v_mul_f32_e32 v7, 0x43800000, v7
	s_waitcnt lgkmcnt(0)
	v_mul_f32_e32 v17, 0x43800000, v2
	v_mul_f32_e32 v18, 0x43800000, v3
	v_med3_f32 v3, v8, s93, v223
	v_med3_f32 v8, v9, s93, v223
	v_mov_b32_e32 v2, v1
	v_cvt_pk_fp8_f32 v2, v3, v8
	v_med3_f32 v6, v6, s93, v223
	v_med3_f32 v7, v7, s93, v223
	v_mov_b32_e32 v3, v1
	v_cvt_pk_fp8_f32 v3, v6, v7
	v_med3_f32 v4, v4, s93, v223
	v_med3_f32 v5, v5, s93, v223
	v_cvt_pk_fp8_f32 v2, v4, v5 op_sel:[0,0,1]
	v_med3_f32 v4, v17, s93, v223
	v_med3_f32 v5, v18, s93, v223
	v_cvt_pk_fp8_f32 v3, v4, v5 op_sel:[0,0,1]
	v_add_u32_e32 v4, s12, v11
	v_ashrrev_i32_e32 v5, 31, v4
	v_lshlrev_b64 v[4:5], 11, v[4:5]
	v_lshl_add_u64 v[4:5], s[6:7], 0, v[4:5]
	v_lshl_add_u64 v[4:5], v[4:5], 0, s[8:9]
	s_add_i32 s10, s10, s92
	v_lshl_add_u64 v[4:5], v[4:5], 0, v[0:1]
	s_cmpk_lt_i32 s11, 0x500
	global_store_dwordx2 v[4:5], v[2:3], off
	s_cbranch_scc0 .Lcw6_x2
	s_ashr_i32 s8, s11, 31
	s_lshr_b32 s8, s8, 27
	s_add_i32 s8, s11, s8
	s_ashr_i32 s8, s8, 5
	s_lshl_b32 s12, s8, 6
	s_lshl_b32 s9, s8, 11
	v_or_b32_e32 v17, s12, v10
	s_movk_i32 s8, 0xa00
	s_sub_i32 s13, 0, s9
	v_cmp_gt_i32_e32 vcc, s8, v17
	s_waitcnt lgkmcnt(0)
	s_barrier
	s_waitcnt vmcnt(2)
	ds_write2_b32 v14, v208, v209 offset1:1
	ds_write2_b32 v14, v210, v211 offset0:2 offset1:3
	ds_write2_b32 v15, v212, v213 offset1:1
	ds_write2_b32 v15, v214, v215 offset0:2 offset1:3
	s_waitcnt lgkmcnt(0)
	s_barrier
	ds_read2_b32 v[2:3], v16 offset1:65
	ds_read2_b32 v[4:5], v16 offset0:130 offset1:195
	s_add_i32 s8, s10, s13
	s_ashr_i32 s9, s8, 31
	s_add_i32 s11, s11, s33
	s_waitcnt lgkmcnt(1)
	v_mul_f32_e32 v8, 0x43800000, v2
	v_add_u32_e32 v2, 0x400, v16
	ds_read2_b32 v[6:7], v2 offset0:4 offset1:69
	v_mul_f32_e32 v9, 0x43800000, v3
	ds_read2_b32 v[2:3], v2 offset0:134 offset1:199
	s_waitcnt lgkmcnt(2)
	v_mul_f32_e32 v4, 0x43800000, v4
	v_mul_f32_e32 v5, 0x43800000, v5
	s_waitcnt lgkmcnt(1)
	v_mul_f32_e32 v6, 0x43800000, v6
	v_mul_f32_e32 v7, 0x43800000, v7
	s_waitcnt lgkmcnt(0)
	v_mul_f32_e32 v17, 0x43800000, v2
	v_mul_f32_e32 v18, 0x43800000, v3
	v_med3_f32 v3, v8, s93, v223
	v_med3_f32 v8, v9, s93, v223
	v_mov_b32_e32 v2, v1
	v_cvt_pk_fp8_f32 v2, v3, v8
	v_med3_f32 v6, v6, s93, v223
	v_med3_f32 v7, v7, s93, v223
	v_mov_b32_e32 v3, v1
	v_cvt_pk_fp8_f32 v3, v6, v7
	v_med3_f32 v4, v4, s93, v223
	v_med3_f32 v5, v5, s93, v223
	v_cvt_pk_fp8_f32 v2, v4, v5 op_sel:[0,0,1]
	v_med3_f32 v4, v17, s93, v223
	v_med3_f32 v5, v18, s93, v223
	v_cvt_pk_fp8_f32 v3, v4, v5 op_sel:[0,0,1]
	v_add_u32_e32 v4, s12, v11
	v_ashrrev_i32_e32 v5, 31, v4
	v_lshlrev_b64 v[4:5], 11, v[4:5]
	v_lshl_add_u64 v[4:5], s[6:7], 0, v[4:5]
	v_lshl_add_u64 v[4:5], v[4:5], 0, s[8:9]
	s_add_i32 s10, s10, s92
	v_lshl_add_u64 v[4:5], v[4:5], 0, v[0:1]
	s_cmpk_lt_i32 s11, 0x500
	global_store_dwordx2 v[4:5], v[2:3], off
	s_cbranch_scc0 .LBB0_1466
	s_branch .Lcw6_top

;     ...
;   for (int t = blockIdx.x; t < ntk * ntn; t += gridDim.x) {
;     const int tk = t % ntk, tn = t / ntk, k0 = tk * 64, n0 = tn * 64;
;     __syncthreads();
; #pragma unroll
;     for (int i = 0; i < 2; ++i) {
;       const int id = tid + 512 * i, kr = id >> 4, n4 = (id & 15) * 4;
;       f32x4 v = {0.f, 0.f, 0.f, 0.f};
;       const int nd = n0 + n4, nsrc = (nvalid < 0) ? nd : (nd < csplit ? nd + coff1 : nd + coff2);
;       if (nd < ((nvalid < 0) ? N : nvalid)) v = *(const f32x4*)(W + (size_t)(k0 + kr) * N + nsrc);
;       tile[kr * 65 + n4 + 0] = v[0]; tile[kr * 65 + n4 + 1] = v[1]; tile[kr * 65 + n4 + 2] = v[2]; tile[kr * 65 + n4 + 3] = v[3];
;     }
;     __syncthreads();
;     {
;       const int n = tid >> 3, c = tid & 7;
;       bool rot = false;
;       if (PERM == 1) rot = (n0 == rot_n0);
;       if (PERM == 2) rot = ((tn % 3) == 2);
;       const int ns = rot ? ((n >> 1) + 32 * (n & 1)) : n;
;       if (FP8) {
;         float f[8];
; #pragma unroll
;         for (int j = 0; j < 8; ++j) f[j] = tile[(c * 8 + j) * 65 + ns] * wscale;
;         u32x2 o = {pk4_fp8(f[0], f[1], f[2], f[3]), pk4_fp8(f[4], f[5], f[6], f[7])};
;         *(u32x2*)((unsigned char*)Wt + (size_t)(n0 + n) * K + k0 + c * 8) = o;
;       } else {
;         u32x4 o;
; #pragma unroll
;         for (int j = 0; j < 4; ++j) o[j] = pk2(tile[(c * 8 + 2 * j) * 65 + ns], tile[(c * 8 + 2 * j + 1) * 65 + ns]);
;         *(u32x4*)(Wt + (size_t)(n0 + n) * K + k0 + c * 8) = o;
;       }
;     }
.Lcw7_top:
	s_mov_b32 s100, s11
	s_mov_b32 s101, s10
	s_ashr_i32 s8, s100, 31
	s_lshr_b32 s8, s8, 29
	s_add_i32 s8, s100, s8
	s_ashr_i32 s8, s8, 3
	s_lshl_b32 s12, s8, 6
	s_lshl_b32 s9, s8, 9
	v_or_b32_e32 v10, s12, v12
	s_movk_i32 s8, 0x1000
	s_sub_i32 s13, 0, s9
	v_cmp_gt_i32_e32 vcc, s8, v10
	v_mov_b32_e32 v98, 0
	v_mov_b32_e32 v99, 0
	v_mov_b32_e32 v100, 0
	v_mov_b32_e32 v101, 0
	v_mov_b32_e32 v102, 0
	v_mov_b32_e32 v103, 0
	v_mov_b32_e32 v104, 0
	v_mov_b32_e32 v105, 0
	s_and_saveexec_b64 s[8:9], vcc
	s_add_i32 s14, s13, s101
	v_add_u32_e32 v116, s14, v15
	v_add_u32_e32 v122, s14, v16
	v_ashrrev_i32_e32 v117, 31, v116
	v_ashrrev_i32_e32 v123, 31, v122
	v_lshlrev_b64 v[116:117], 14, v[116:117]
	v_ashrrev_i32_e32 v11, 31, v10
	v_lshlrev_b64 v[122:123], 14, v[122:123]
	v_lshl_add_u64 v[116:117], s[0:1], 0, v[116:117]
	v_lshlrev_b64 v[118:119], 2, v[10:11]
	v_lshl_add_u64 v[122:123], s[0:1], 0, v[122:123]
	v_lshl_add_u64 v[116:117], v[116:117], 0, v[118:119]
	v_lshl_add_u64 v[118:119], v[122:123], 0, v[118:119]
	global_load_dwordx4 v[98:101], v[116:117], off
	s_nop 0
	global_load_dwordx4 v[102:105], v[118:119], off
	s_or_b64 exec, exec, s[8:9]
	s_add_i32 s100, s100, s33
	s_add_i32 s101, s101, s92
	s_cmpk_lt_i32 s100, 0x200
	s_cselect_b32 s100, s100, s11
	s_cselect_b32 s101, s101, s10
	s_ashr_i32 s8, s100, 31
	s_lshr_b32 s8, s8, 29
	s_add_i32 s8, s100, s8
	s_ashr_i32 s8, s8, 3
	s_lshl_b32 s12, s8, 6
	s_lshl_b32 s9, s8, 9
	v_or_b32_e32 v10, s12, v12
	s_movk_i32 s8, 0x1000
	s_sub_i32 s13, 0, s9
	v_cmp_gt_i32_e32 vcc, s8, v10
	v_mov_b32_e32 v106, 0
	v_mov_b32_e32 v107, 0
	v_mov_b32_e32 v108, 0
	v_mov_b32_e32 v109, 0
	v_mov_b32_e32 v110, 0
	v_mov_b32_e32 v111, 0
	v_mov_b32_e32 v112, 0
	v_mov_b32_e32 v113, 0
	s_and_saveexec_b64 s[8:9], vcc
	s_add_i32 s14, s13, s101
	v_add_u32_e32 v116, s14, v15
	v_add_u32_e32 v122, s14, v16
	v_ashrrev_i32_e32 v117, 31, v116
	v_ashrrev_i32_e32 v123, 31, v122
	v_lshlrev_b64 v[116:117], 14, v[116:117]
	v_ashrrev_i32_e32 v11, 31, v10
	v_lshlrev_b64 v[122:123], 14, v[122:123]
	v_lshl_add_u64 v[116:117], s[0:1], 0, v[116:117]
	v_lshlrev_b64 v[118:119], 2, v[10:11]
	v_lshl_add_u64 v[122:123], s[0:1], 0, v[122:123]
	v_lshl_add_u64 v[116:117], v[116:117], 0, v[118:119]
	v_lshl_add_u64 v[118:119], v[122:123], 0, v[118:119]
	global_load_dwordx4 v[106:109], v[116:117], off
	s_nop 0
	global_load_dwordx4 v[110:113], v[118:119], off
	s_or_b64 exec, exec, s[8:9]
	s_add_i32 s100, s100, s33
	s_add_i32 s101, s101, s92
	s_cmpk_lt_i32 s100, 0x200
	s_cselect_b32 s100, s100, s11
	s_cselect_b32 s101, s101, s10
	s_ashr_i32 s8, s100, 31
	s_lshr_b32 s8, s8, 29
	s_add_i32 s8, s100, s8
	s_ashr_i32 s8, s8, 3
	s_lshl_b32 s12, s8, 6
	s_lshl_b32 s9, s8, 9
	v_or_b32_e32 v10, s12, v12
	s_movk_i32 s8, 0x1000
	s_sub_i32 s13, 0, s9
	v_cmp_gt_i32_e32 vcc, s8, v10
	v_mov_b32_e32 v208, 0
	v_mov_b32_e32 v209, 0
	v_mov_b32_e32 v210, 0
	v_mov_b32_e32 v211, 0
	v_mov_b32_e32 v212, 0
	v_mov_b32_e32 v213, 0
	v_mov_b32_e32 v214, 0
	v_mov_b32_e32 v215, 0
	s_and_saveexec_b64 s[8:9], vcc
	s_add_i32 s14, s13, s101
	v_add_u32_e32 v116, s14, v15
	v_add_u32_e32 v122, s14, v16
	v_ashrrev_i32_e32 v117, 31, v116
	v_ashrrev_i32_e32 v123, 31, v122
	v_lshlrev_b64 v[116:117], 14, v[116:117]
	v_ashrrev_i32_e32 v11, 31, v10
	v_lshlrev_b64 v[122:123], 14, v[122:123]
	v_lshl_add_u64 v[116:117], s[0:1], 0, v[116:117]
	v_lshlrev_b64 v[118:119], 2, v[10:11]
	v_lshl_add_u64 v[122:123], s[0:1], 0, v[122:123]
	v_lshl_add_u64 v[116:117], v[116:117], 0, v[118:119]
	v_lshl_add_u64 v[118:119], v[122:123], 0, v[118:119]
	global_load_dwordx4 v[208:211], v[116:117], off
	s_nop 0
	global_load_dwordx4 v[212:215], v[118:119], off
	s_or_b64 exec, exec, s[8:9]
	s_ashr_i32 s8, s11, 31
	s_lshr_b32 s8, s8, 29
	s_add_i32 s8, s11, s8
	s_ashr_i32 s8, s8, 3
	s_lshl_b32 s12, s8, 6
	s_lshl_b32 s9, s8, 9
	v_or_b32_e32 v10, s12, v12
	s_movk_i32 s8, 0x1000
	s_sub_i32 s13, 0, s9
	v_cmp_gt_i32_e32 vcc, s8, v10
	s_waitcnt lgkmcnt(0)
	s_barrier
;     ...
;   for (int t = blockIdx.x; t < ntk * ntn; t += gridDim.x) {
;     const int tk = t % ntk, tn = t / ntk, k0 = tk * 64, n0 = tn * 64;
;     __syncthreads();
; #pragma unroll
;     for (int i = 0; i < 2; ++i) {
;       const int id = tid + 512 * i, kr = id >> 4, n4 = (id & 15) * 4;
;       f32x4 v = {0.f, 0.f, 0.f, 0.f};
;       const int nd = n0 + n4, nsrc = (nvalid < 0) ? nd : (nd < csplit ? nd + coff1 : nd + coff2);
;       if (nd < ((nvalid < 0) ? N : nvalid)) v = *(const f32x4*)(W + (size_t)(k0 + kr) * N + nsrc);
;       tile[kr * 65 + n4 + 0] = v[0]; tile[kr * 65 + n4 + 1] = v[1]; tile[kr * 65 + n4 + 2] = v[2]; tile[kr * 65 + n4 + 3] = v[3];
;     }
;     __syncthreads();
;     {
;       const int n = tid >> 3, c = tid & 7;
;       bool rot = false;
;       if (PERM == 1) rot = (n0 == rot_n0);
;       if (PERM == 2) rot = ((tn % 3) == 2);
;       const int ns = rot ? ((n >> 1) + 32 * (n & 1)) : n;
;       if (FP8) {
;         float f[8];
; #pragma unroll
;         for (int j = 0; j < 8; ++j) f[j] = tile[(c * 8 + j) * 65 + ns] * wscale;
;         u32x2 o = {pk4_fp8(f[0], f[1], f[2], f[3]), pk4_fp8(f[4], f[5], f[6], f[7])};
;         *(u32x2*)((unsigned char*)Wt + (size_t)(n0 + n) * K + k0 + c * 8) = o;
;       } else {
;         u32x4 o;
; #pragma unroll
;         for (int j = 0; j < 4; ++j) o[j] = pk2(tile[(c * 8 + 2 * j) * 65 + ns], tile[(c * 8 + 2 * j + 1) * 65 + ns]);
;         *(u32x4*)(Wt + (size_t)(n0 + n) * K + k0 + c * 8) = o;
;       }
;     }
	s_waitcnt vmcnt(4)
	ds_write2_b32 v18, v98, v99 offset1:1
	ds_write2_b32 v18, v100, v101 offset0:2 offset1:3
	ds_write2_b32 v19, v102, v103 offset1:1
	ds_write2_b32 v19, v104, v105 offset0:2 offset1:3
	s_waitcnt lgkmcnt(0)
	s_barrier
	ds_read2_b32 v[2:3], v14 offset1:130
	ds_read2_b32 v[4:5], v17 offset0:65 offset1:195
	v_add_u32_e32 v6, 0x400, v17
	ds_read2_b32 v[6:7], v6 offset0:69 offset1:199
	s_add_i32 s8, s10, s13
	s_ashr_i32 s9, s8, 31
	s_waitcnt lgkmcnt(1)
	v_cvt_pk_bf16_f32 v2, v2, v4
	v_add_u32_e32 v4, 0x400, v14
	v_cvt_pk_bf16_f32 v3, v3, v5
	ds_read2_b32 v[4:5], v4 offset0:4 offset1:134
	s_add_i32 s11, s11, s33
	s_add_i32 s10, s10, s92
	s_cmpk_gt_i32 s11, 0x1ff
	s_waitcnt lgkmcnt(0)
	v_cvt_pk_bf16_f32 v4, v4, v6
	v_add_u32_e32 v6, s12, v13
	v_cvt_pk_bf16_f32 v5, v5, v7
	v_ashrrev_i32_e32 v7, 31, v6
	v_readlane_b32 s12, v253, 53
	v_lshlrev_b64 v[6:7], 10, v[6:7]
	v_readlane_b32 s13, v253, 54
	s_nop 1
	v_lshl_add_u64 v[6:7], s[12:13], 0, v[6:7]
	v_lshl_add_u64 v[6:7], s[8:9], 1, v[6:7]
	v_lshl_add_u64 v[6:7], v[6:7], 0, v[0:1]
	global_store_dwordx4 v[6:7], v[2:5], off
	s_cbranch_scc1 .Lcw7_x1
	s_ashr_i32 s8, s11, 31
	s_lshr_b32 s8, s8, 29
	s_add_i32 s8, s11, s8
	s_ashr_i32 s8, s8, 3
	s_lshl_b32 s12, s8, 6
	s_lshl_b32 s9, s8, 9
	v_or_b32_e32 v10, s12, v12
	s_movk_i32 s8, 0x1000
	s_sub_i32 s13, 0, s9
	v_cmp_gt_i32_e32 vcc, s8, v10
	s_waitcnt lgkmcnt(0)
	s_barrier
	s_waitcnt vmcnt(3)
	ds_write2_b32 v18, v106, v107 offset1:1
	ds_write2_b32 v18, v108, v109 offset0:2 offset1:3
	ds_write2_b32 v19, v110, v111 offset1:1
	ds_write2_b32 v19, v112, v113 offset0:2 offset1:3
	s_waitcnt lgkmcnt(0)
	s_barrier
	ds_read2_b32 v[2:3], v14 offset1:130
	ds_read2_b32 v[4:5], v17 offset0:65 offset1:195
	v_add_u32_e32 v6, 0x400, v17
	ds_read2_b32 v[6:7], v6 offset0:69 offset1:199
	s_add_i32 s8, s10, s13
	s_ashr_i32 s9, s8, 31
	s_waitcnt lgkmcnt(1)
	v_cvt_pk_bf16_f32 v2, v2, v4
	v_add_u32_e32 v4, 0x400, v14
	v_cvt_pk_bf16_f32 v3, v3, v5
	ds_read2_b32 v[4:5], v4 offset0:4 offset1:134
	s_add_i32 s11, s11, s33
	s_add_i32 s10, s10, s92
	s_cmpk_gt_i32 s11, 0x1ff
	s_waitcnt lgkmcnt(0)
	v_cvt_pk_bf16_f32 v4, v4, v6
	v_add_u32_e32 v6, s12, v13
	v_cvt_pk_bf16_f32 v5, v5, v7
	v_ashrrev_i32_e32 v7, 31, v6
	v_readlane_b32 s12, v253, 53
	v_lshlrev_b64 v[6:7], 10, v[6:7]
	v_readlane_b32 s13, v253, 54
	s_nop 1
	v_lshl_add_u64 v[6:7], s[12:13], 0, v[6:7]
	v_lshl_add_u64 v[6:7], s[8:9], 1, v[6:7]
	v_lshl_add_u64 v[6:7], v[6:7], 0, v[0:1]
	global_store_dwordx4 v[6:7], v[2:5], off
	s_cbranch_scc1 .Lcw7_x2
	s_ashr_i32 s8, s11, 31
	s_lshr_b32 s8, s8, 29
	s_add_i32 s8, s11, s8
	s_ashr_i32 s8, s8, 3
	s_lshl_b32 s12, s8, 6
	s_lshl_b32 s9, s8, 9
	v_or_b32_e32 v10, s12, v12
	s_movk_i32 s8, 0x1000
	s_sub_i32 s13, 0, s9
	v_cmp_gt_i32_e32 vcc, s8, v10
	s_waitcnt lgkmcnt(0)
	s_barrier
	s_waitcnt vmcnt(2)
	ds_write2_b32 v18, v208, v209 offset1:1
	ds_write2_b32 v18, v210, v211 offset0:2 offset1:3
	ds_write2_b32 v19, v212, v213 offset1:1
	ds_write2_b32 v19, v214, v215 offset0:2 offset1:3
	s_waitcnt lgkmcnt(0)
	s_barrier
	ds_read2_b32 v[2:3], v14 offset1:130
	ds_read2_b32 v[4:5], v17 offset0:65 offset1:195
	v_add_u32_e32 v6, 0x400, v17
	ds_read2_b32 v[6:7], v6 offset0:69 offset1:199
	s_add_i32 s8, s10, s13
	s_ashr_i32 s9, s8, 31
	s_waitcnt lgkmcnt(1)
	v_cvt_pk_bf16_f32 v2, v2, v4
	v_add_u32_e32 v4, 0x400, v14
	v_cvt_pk_bf16_f32 v3, v3, v5
	ds_read2_b32 v[4:5], v4 offset0:4 offset1:134
	s_add_i32 s11, s11, s33
	s_add_i32 s10, s10, s92
	s_cmpk_gt_i32 s11, 0x1ff
	s_waitcnt lgkmcnt(0)
	v_cvt_pk_bf16_f32 v4, v4, v6
	v_add_u32_e32 v6, s12, v13
	v_cvt_pk_bf16_f32 v5, v5, v7
	v_ashrrev_i32_e32 v7, 31, v6
	v_readlane_b32 s12, v253, 53
	v_lshlrev_b64 v[6:7], 10, v[6:7]
	v_readlane_b32 s13, v253, 54
	s_nop 1
	v_lshl_add_u64 v[6:7], s[12:13], 0, v[6:7]
	v_lshl_add_u64 v[6:7], s[8:9], 1, v[6:7]
	v_lshl_add_u64 v[6:7], v[6:7], 0, v[0:1]
	global_store_dwordx4 v[6:7], v[2:5], off
	s_cbranch_scc1 .LBB0_1475
	s_branch .Lcw7_top
